# MFMA runs of the GEMM K-loops padded to 8-byte alignment (s_nop before each misaligned run), on top of the P0 item pipeline
# baseline (speedup 1.0000x reference)
.LBB0_446:
	ds_read_b128 v[148:151], v165
	ds_read_b128 v[174:177], v165 offset:1024
	ds_read_b128 v[180:183], v165 offset:2048
	ds_read_b128 v[184:187], v165 offset:3072
	ds_read_b128 v[188:191], v169
	ds_read_b128 v[192:195], v169 offset:1024
	ds_read_b128 v[196:199], v169 offset:2048
	ds_read_b128 v[200:203], v169 offset:3072
	s_add_u32 s50, s4, 0xfff00080
	s_addc_u32 s51, s5, -1
	s_cmp_eq_u32 s68, 60
	s_cselect_b32 s53, s3, s51
	s_cselect_b32 s52, s8, s50
	s_cselect_b32 s51, s39, s65
	s_cselect_b32 s50, s45, s63
	v_lshl_add_u64 v[154:155], s[4:5], 0, v[140:141]
	s_add_i32 m0, s7, 0xc000
	ds_read_b128 v[204:207], v173
	ds_read_b128 v[208:211], v173 offset:1024
	ds_read_b128 v[212:215], v173 offset:2048
	ds_read_b128 v[216:219], v173 offset:3072
	ds_read_b128 v[220:223], v173 offset:4096
	ds_read_b128 v[224:227], v173 offset:5120
	ds_read_b128 v[228:231], v173 offset:6144
	ds_read_b128 v[236:239], v173 offset:7168
	global_load_lds_dwordx4 v[154:155], off
	v_lshl_add_u64 v[154:155], s[4:5], 0, v[142:143]
	s_add_i32 m0, s7, 0xe000
	s_nop 0
	global_load_lds_dwordx4 v[154:155], off
	s_waitcnt vmcnt(8)
	s_waitcnt lgkmcnt(0)
	s_barrier
	s_nop 0
	s_setprio 1
	s_waitcnt lgkmcnt(0)
	v_mfma_f32_16x16x32_bf16 v[126:129], v[148:151], v[204:207], v[126:129]
	v_mfma_f32_16x16x32_bf16 v[122:125], v[180:183], v[204:207], v[122:125]
	v_mfma_f32_16x16x32_bf16 v[110:113], v[148:151], v[212:215], v[110:113]
	v_mfma_f32_16x16x32_bf16 v[106:109], v[180:183], v[212:215], v[106:109]
	v_mfma_f32_16x16x32_bf16 v[94:97], v[148:151], v[220:223], v[94:97]
	v_mfma_f32_16x16x32_bf16 v[90:93], v[180:183], v[220:223], v[90:93]
	v_mfma_f32_16x16x32_bf16 v[78:81], v[148:151], v[228:231], v[78:81]
	v_mfma_f32_16x16x32_bf16 v[74:77], v[180:183], v[228:231], v[74:77]
	v_mfma_f32_16x16x32_bf16 v[126:129], v[174:177], v[208:211], v[126:129]
	v_mfma_f32_16x16x32_bf16 v[122:125], v[184:187], v[208:211], v[122:125]
	v_mfma_f32_16x16x32_bf16 v[110:113], v[174:177], v[216:219], v[110:113]
	v_mfma_f32_16x16x32_bf16 v[106:109], v[184:187], v[216:219], v[106:109]
	v_mfma_f32_16x16x32_bf16 v[94:97], v[174:177], v[224:227], v[94:97]
	v_mfma_f32_16x16x32_bf16 v[90:93], v[184:187], v[224:227], v[90:93]
	v_mfma_f32_16x16x32_bf16 v[78:81], v[174:177], v[236:239], v[78:81]
	v_mfma_f32_16x16x32_bf16 v[74:77], v[184:187], v[236:239], v[74:77]
	s_setprio 0
	s_setprio 1
	v_mfma_f32_16x16x32_bf16 v[118:121], v[188:191], v[204:207], v[118:121]
	v_mfma_f32_16x16x32_bf16 v[114:117], v[196:199], v[204:207], v[114:117]
	v_mfma_f32_16x16x32_bf16 v[102:105], v[188:191], v[212:215], v[102:105]
	v_mfma_f32_16x16x32_bf16 v[98:101], v[196:199], v[212:215], v[98:101]
	v_mfma_f32_16x16x32_bf16 v[86:89], v[188:191], v[220:223], v[86:89]
	v_mfma_f32_16x16x32_bf16 v[82:85], v[196:199], v[220:223], v[82:85]
	v_mfma_f32_16x16x32_bf16 v[70:73], v[188:191], v[228:231], v[70:73]
	v_mfma_f32_16x16x32_bf16 v[66:69], v[196:199], v[228:231], v[66:69]
	v_mfma_f32_16x16x32_bf16 v[118:121], v[192:195], v[208:211], v[118:121]
	v_mfma_f32_16x16x32_bf16 v[114:117], v[200:203], v[208:211], v[114:117]
	v_mfma_f32_16x16x32_bf16 v[102:105], v[192:195], v[216:219], v[102:105]
	v_mfma_f32_16x16x32_bf16 v[98:101], v[200:203], v[216:219], v[98:101]
	v_mfma_f32_16x16x32_bf16 v[86:89], v[192:195], v[224:227], v[86:89]
	v_mfma_f32_16x16x32_bf16 v[82:85], v[200:203], v[224:227], v[82:85]
	v_mfma_f32_16x16x32_bf16 v[70:73], v[192:195], v[236:239], v[70:73]
	v_mfma_f32_16x16x32_bf16 v[66:69], v[200:203], v[236:239], v[66:69]
	s_setprio 0
	s_barrier
	s_add_i32 s69, s59, s35
	v_lshl_add_u64 v[154:155], s[50:51], 0, v[132:133]
	s_mov_b32 m0, s69
	ds_read_b128 v[204:207], v173 offset:16384
	ds_read_b128 v[208:211], v173 offset:17408
	ds_read_b128 v[212:215], v173 offset:18432
	ds_read_b128 v[216:219], v173 offset:19456
	ds_read_b128 v[220:223], v173 offset:20480
	ds_read_b128 v[224:227], v173 offset:21504
	ds_read_b128 v[228:231], v173 offset:22528
	ds_read_b128 v[236:239], v173 offset:23552
	global_load_lds_dwordx4 v[154:155], off
	s_add_i32 m0, s69, 0x2000
	s_add_u32 s70, s50, 0x100000
	v_lshl_add_u64 v[158:159], s[50:51], 0, v[136:137]
	s_addc_u32 s71, s51, 0
	s_add_i32 s69, s60, s35
	global_load_lds_dwordx4 v[158:159], off
	v_lshl_add_u64 v[162:163], s[70:71], 0, v[132:133]
	s_mov_b32 m0, s69
	v_lshl_add_u64 v[166:167], s[52:53], 0, v[134:135]
	global_load_lds_dwordx4 v[162:163], off
	v_lshl_add_u64 v[162:163], s[70:71], 0, v[136:137]
	s_add_i32 m0, s69, 0x2000
	s_nop 0
	global_load_lds_dwordx4 v[162:163], off
	v_lshl_add_u64 v[162:163], s[52:53], 0, v[130:131]
	s_mov_b32 m0, s7
	s_nop 0
	global_load_lds_dwordx4 v[162:163], off
	s_mov_b32 m0, s37
	s_nop 0
	global_load_lds_dwordx4 v[166:167], off
	s_waitcnt vmcnt(8)
	s_waitcnt lgkmcnt(0)
	s_barrier
	s_nop 0
	s_setprio 1
	s_waitcnt lgkmcnt(0)
	v_mfma_f32_16x16x32_bf16 v[62:65], v[148:151], v[204:207], v[62:65]
	v_mfma_f32_16x16x32_bf16 v[58:61], v[180:183], v[204:207], v[58:61]
	v_mfma_f32_16x16x32_bf16 v[46:49], v[148:151], v[212:215], v[46:49]
	v_mfma_f32_16x16x32_bf16 v[42:45], v[180:183], v[212:215], v[42:45]
	v_mfma_f32_16x16x32_bf16 v[30:33], v[148:151], v[220:223], v[30:33]
	v_mfma_f32_16x16x32_bf16 v[26:29], v[180:183], v[220:223], v[26:29]
	v_mfma_f32_16x16x32_bf16 v[14:17], v[148:151], v[228:231], v[14:17]
	v_mfma_f32_16x16x32_bf16 v[10:13], v[180:183], v[228:231], v[10:13]
	v_mfma_f32_16x16x32_bf16 v[62:65], v[174:177], v[208:211], v[62:65]
	v_mfma_f32_16x16x32_bf16 v[58:61], v[184:187], v[208:211], v[58:61]
	v_mfma_f32_16x16x32_bf16 v[46:49], v[174:177], v[216:219], v[46:49]
	v_mfma_f32_16x16x32_bf16 v[42:45], v[184:187], v[216:219], v[42:45]
	v_mfma_f32_16x16x32_bf16 v[30:33], v[174:177], v[224:227], v[30:33]
	v_mfma_f32_16x16x32_bf16 v[26:29], v[184:187], v[224:227], v[26:29]
	v_mfma_f32_16x16x32_bf16 v[14:17], v[174:177], v[236:239], v[14:17]
	v_mfma_f32_16x16x32_bf16 v[10:13], v[184:187], v[236:239], v[10:13]
	s_setprio 0
	s_setprio 1
	v_mfma_f32_16x16x32_bf16 v[54:57], v[188:191], v[204:207], v[54:57]
	v_mfma_f32_16x16x32_bf16 v[50:53], v[196:199], v[204:207], v[50:53]
	v_mfma_f32_16x16x32_bf16 v[38:41], v[188:191], v[212:215], v[38:41]
	v_mfma_f32_16x16x32_bf16 v[34:37], v[196:199], v[212:215], v[34:37]
	v_mfma_f32_16x16x32_bf16 v[22:25], v[188:191], v[220:223], v[22:25]
	v_mfma_f32_16x16x32_bf16 v[18:21], v[196:199], v[220:223], v[18:21]
	v_mfma_f32_16x16x32_bf16 v[6:9], v[188:191], v[228:231], v[6:9]
	v_mfma_f32_16x16x32_bf16 v[2:5], v[196:199], v[228:231], v[2:5]
	v_mfma_f32_16x16x32_bf16 v[54:57], v[192:195], v[208:211], v[54:57]
	v_mfma_f32_16x16x32_bf16 v[50:53], v[200:203], v[208:211], v[50:53]
	v_mfma_f32_16x16x32_bf16 v[38:41], v[192:195], v[216:219], v[38:41]
	v_mfma_f32_16x16x32_bf16 v[34:37], v[200:203], v[216:219], v[34:37]
	v_mfma_f32_16x16x32_bf16 v[22:25], v[192:195], v[224:227], v[22:25]
	v_mfma_f32_16x16x32_bf16 v[18:21], v[200:203], v[224:227], v[18:21]
	v_mfma_f32_16x16x32_bf16 v[6:9], v[192:195], v[236:239], v[6:9]
	v_mfma_f32_16x16x32_bf16 v[2:5], v[200:203], v[236:239], v[2:5]
	s_setprio 0
	s_barrier
	s_add_i32 s69, 0, 0x18000
	v_add_u32_e32 v139, s69, v161
	s_add_i32 s70, 0, 0x1c000
	ds_read_b128 v[148:151], v139
	ds_read_b128 v[174:177], v139 offset:1024
	ds_read_b128 v[180:183], v139 offset:2048
	ds_read_b128 v[184:187], v139 offset:3072
	v_add_u32_e32 v139, s70, v161
	ds_read_b128 v[188:191], v139
	ds_read_b128 v[192:195], v139 offset:1024
	ds_read_b128 v[196:199], v139 offset:2048
	ds_read_b128 v[200:203], v139 offset:3072
	s_add_u32 s52, s52, 0x100000
	s_addc_u32 s53, s53, 0
	s_mov_b32 m0, s41
	v_lshl_add_u64 v[170:171], s[52:53], 0, v[130:131]
	ds_read_b128 v[204:207], v173 offset:32768
	ds_read_b128 v[208:211], v173 offset:33792
	ds_read_b128 v[212:215], v173 offset:34816
	ds_read_b128 v[216:219], v173 offset:35840
	ds_read_b128 v[220:223], v173 offset:36864
	ds_read_b128 v[224:227], v173 offset:37888
	ds_read_b128 v[228:231], v173 offset:38912
	ds_read_b128 v[236:239], v173 offset:39936
	global_load_lds_dwordx4 v[170:171], off
	v_lshl_add_u64 v[170:171], s[52:53], 0, v[134:135]
	s_mov_b32 m0, s43
	s_nop 0
	global_load_lds_dwordx4 v[170:171], off
	s_waitcnt vmcnt(8)
	s_waitcnt lgkmcnt(0)
	s_barrier
	s_nop 0
	s_setprio 1
	s_waitcnt lgkmcnt(0)
	v_mfma_f32_16x16x32_bf16 v[126:129], v[148:151], v[204:207], v[126:129]
	v_mfma_f32_16x16x32_bf16 v[122:125], v[180:183], v[204:207], v[122:125]
	v_mfma_f32_16x16x32_bf16 v[110:113], v[148:151], v[212:215], v[110:113]
	v_mfma_f32_16x16x32_bf16 v[106:109], v[180:183], v[212:215], v[106:109]
	v_mfma_f32_16x16x32_bf16 v[94:97], v[148:151], v[220:223], v[94:97]
	v_mfma_f32_16x16x32_bf16 v[90:93], v[180:183], v[220:223], v[90:93]
	v_mfma_f32_16x16x32_bf16 v[78:81], v[148:151], v[228:231], v[78:81]
	v_mfma_f32_16x16x32_bf16 v[74:77], v[180:183], v[228:231], v[74:77]
	v_mfma_f32_16x16x32_bf16 v[126:129], v[174:177], v[208:211], v[126:129]
	v_mfma_f32_16x16x32_bf16 v[122:125], v[184:187], v[208:211], v[122:125]
	v_mfma_f32_16x16x32_bf16 v[110:113], v[174:177], v[216:219], v[110:113]
	v_mfma_f32_16x16x32_bf16 v[106:109], v[184:187], v[216:219], v[106:109]
	v_mfma_f32_16x16x32_bf16 v[94:97], v[174:177], v[224:227], v[94:97]
	v_mfma_f32_16x16x32_bf16 v[90:93], v[184:187], v[224:227], v[90:93]
	v_mfma_f32_16x16x32_bf16 v[78:81], v[174:177], v[236:239], v[78:81]
	v_mfma_f32_16x16x32_bf16 v[74:77], v[184:187], v[236:239], v[74:77]
	s_setprio 0
	s_setprio 1
	v_mfma_f32_16x16x32_bf16 v[118:121], v[188:191], v[204:207], v[118:121]
	v_mfma_f32_16x16x32_bf16 v[114:117], v[196:199], v[204:207], v[114:117]
	v_mfma_f32_16x16x32_bf16 v[102:105], v[188:191], v[212:215], v[102:105]
	v_mfma_f32_16x16x32_bf16 v[98:101], v[196:199], v[212:215], v[98:101]
	v_mfma_f32_16x16x32_bf16 v[86:89], v[188:191], v[220:223], v[86:89]
	v_mfma_f32_16x16x32_bf16 v[82:85], v[196:199], v[220:223], v[82:85]
	v_mfma_f32_16x16x32_bf16 v[70:73], v[188:191], v[228:231], v[70:73]
	v_mfma_f32_16x16x32_bf16 v[66:69], v[196:199], v[228:231], v[66:69]
	v_mfma_f32_16x16x32_bf16 v[118:121], v[192:195], v[208:211], v[118:121]
	v_mfma_f32_16x16x32_bf16 v[114:117], v[200:203], v[208:211], v[114:117]
	v_mfma_f32_16x16x32_bf16 v[102:105], v[192:195], v[216:219], v[102:105]
	v_mfma_f32_16x16x32_bf16 v[98:101], v[200:203], v[216:219], v[98:101]
	v_mfma_f32_16x16x32_bf16 v[86:89], v[192:195], v[224:227], v[86:89]
	v_mfma_f32_16x16x32_bf16 v[82:85], v[200:203], v[224:227], v[82:85]
	v_mfma_f32_16x16x32_bf16 v[70:73], v[192:195], v[236:239], v[70:73]
	v_mfma_f32_16x16x32_bf16 v[66:69], v[200:203], v[236:239], v[66:69]
	s_setprio 0
	s_barrier
	s_add_i32 s52, s69, s35
	v_lshl_add_u64 v[154:155], v[154:155], 0, s[16:17]
	s_mov_b32 m0, s52
	ds_read_b128 v[204:207], v173 offset:49152
	ds_read_b128 v[208:211], v173 offset:50176
	ds_read_b128 v[212:215], v173 offset:51200
	ds_read_b128 v[216:219], v173 offset:52224
	ds_read_b128 v[220:223], v173 offset:53248
	ds_read_b128 v[224:227], v173 offset:54272
	ds_read_b128 v[228:231], v173 offset:55296
	ds_read_b128 v[236:239], v173 offset:56320
	global_load_lds_dwordx4 v[154:155], off
	s_add_i32 m0, s52, 0x2000
	s_add_u32 s50, s50, 0x100080
	v_lshl_add_u64 v[154:155], v[158:159], 0, s[16:17]
	s_addc_u32 s51, s51, 0
	s_add_i32 s52, s70, s35
	global_load_lds_dwordx4 v[154:155], off
	v_lshl_add_u64 v[154:155], s[50:51], 0, v[132:133]
	s_mov_b32 m0, s52
	s_nop 0
	global_load_lds_dwordx4 v[154:155], off
	v_lshl_add_u64 v[154:155], s[50:51], 0, v[136:137]
	s_add_i32 m0, s52, 0x2000
	s_nop 0
	global_load_lds_dwordx4 v[154:155], off
	v_lshl_add_u64 v[154:155], v[162:163], 0, s[16:17]
	s_mov_b32 m0, s57
	s_nop 0
	global_load_lds_dwordx4 v[154:155], off
	v_lshl_add_u64 v[154:155], v[166:167], 0, s[16:17]
	s_mov_b32 m0, s58
	s_nop 0
	global_load_lds_dwordx4 v[154:155], off
	s_waitcnt vmcnt(8)
	s_waitcnt lgkmcnt(0)
	s_barrier
	s_setprio 1
	s_waitcnt lgkmcnt(0)
	v_mfma_f32_16x16x32_bf16 v[62:65], v[148:151], v[204:207], v[62:65]
	v_mfma_f32_16x16x32_bf16 v[58:61], v[180:183], v[204:207], v[58:61]
	v_mfma_f32_16x16x32_bf16 v[46:49], v[148:151], v[212:215], v[46:49]
	v_mfma_f32_16x16x32_bf16 v[42:45], v[180:183], v[212:215], v[42:45]
	v_mfma_f32_16x16x32_bf16 v[30:33], v[148:151], v[220:223], v[30:33]
	v_mfma_f32_16x16x32_bf16 v[26:29], v[180:183], v[220:223], v[26:29]
	v_mfma_f32_16x16x32_bf16 v[14:17], v[148:151], v[228:231], v[14:17]
	v_mfma_f32_16x16x32_bf16 v[10:13], v[180:183], v[228:231], v[10:13]
	v_mfma_f32_16x16x32_bf16 v[62:65], v[174:177], v[208:211], v[62:65]
	v_mfma_f32_16x16x32_bf16 v[58:61], v[184:187], v[208:211], v[58:61]
	v_mfma_f32_16x16x32_bf16 v[46:49], v[174:177], v[216:219], v[46:49]
	v_mfma_f32_16x16x32_bf16 v[42:45], v[184:187], v[216:219], v[42:45]
	v_mfma_f32_16x16x32_bf16 v[30:33], v[174:177], v[224:227], v[30:33]
	v_mfma_f32_16x16x32_bf16 v[26:29], v[184:187], v[224:227], v[26:29]
	v_mfma_f32_16x16x32_bf16 v[14:17], v[174:177], v[236:239], v[14:17]
	v_mfma_f32_16x16x32_bf16 v[10:13], v[184:187], v[236:239], v[10:13]
	s_setprio 0
	s_setprio 1
	v_mfma_f32_16x16x32_bf16 v[54:57], v[188:191], v[204:207], v[54:57]
	v_mfma_f32_16x16x32_bf16 v[50:53], v[196:199], v[204:207], v[50:53]
	v_mfma_f32_16x16x32_bf16 v[38:41], v[188:191], v[212:215], v[38:41]
	v_mfma_f32_16x16x32_bf16 v[34:37], v[196:199], v[212:215], v[34:37]
	v_mfma_f32_16x16x32_bf16 v[22:25], v[188:191], v[220:223], v[22:25]
	v_mfma_f32_16x16x32_bf16 v[18:21], v[196:199], v[220:223], v[18:21]
	v_mfma_f32_16x16x32_bf16 v[6:9], v[188:191], v[228:231], v[6:9]
	v_mfma_f32_16x16x32_bf16 v[2:5], v[196:199], v[228:231], v[2:5]
	v_mfma_f32_16x16x32_bf16 v[54:57], v[192:195], v[208:211], v[54:57]
	v_mfma_f32_16x16x32_bf16 v[50:53], v[200:203], v[208:211], v[50:53]
	v_mfma_f32_16x16x32_bf16 v[38:41], v[192:195], v[216:219], v[38:41]
	v_mfma_f32_16x16x32_bf16 v[34:37], v[200:203], v[216:219], v[34:37]
	v_mfma_f32_16x16x32_bf16 v[22:25], v[192:195], v[224:227], v[22:25]
	v_mfma_f32_16x16x32_bf16 v[18:21], v[200:203], v[224:227], v[18:21]
	v_mfma_f32_16x16x32_bf16 v[6:9], v[192:195], v[236:239], v[6:9]
	v_mfma_f32_16x16x32_bf16 v[2:5], v[200:203], v[236:239], v[2:5]
	s_setprio 0
	s_barrier
	s_add_i32 s68, s68, 2
	s_add_u32 s4, s4, 0x100
	s_addc_u32 s5, s5, 0
	s_add_u32 s63, s63, 0x100
	s_addc_u32 s65, s65, 0
	s_cmp_gt_u32 s68, 61
	s_cbranch_scc0 .LBB0_446
	s_and_b64 vcc, exec, s[20:21]
	s_cbranch_vccz .LBB0_449
	s_barrier

.LBB0_668:
	ds_read_b128 v[154:157], v151
	ds_read_b128 v[158:161], v151 offset:1024
	ds_read_b128 v[162:165], v151 offset:2048
	ds_read_b128 v[166:169], v151 offset:3072
	ds_read_b128 v[170:173], v152
	ds_read_b128 v[174:177], v152 offset:1024
	ds_read_b128 v[178:181], v152 offset:2048
	ds_read_b128 v[182:185], v152 offset:3072
	s_add_u32 s36, s34, 0xfff00080
	s_addc_u32 s37, s35, -1
	s_cmp_eq_u32 s68, 60
	s_cselect_b32 s39, s25, s37
	s_cselect_b32 s38, s61, s36
	s_cselect_b32 s37, s23, s65
	s_cselect_b32 s36, s62, s63
	v_lshl_add_u64 v[148:149], s[34:35], 0, v[140:141]
	s_add_i32 m0, s31, 0xc000
	ds_read_b128 v[186:189], v153
	ds_read_b128 v[190:193], v153 offset:1024
	ds_read_b128 v[194:197], v153 offset:2048
	ds_read_b128 v[198:201], v153 offset:3072
	ds_read_b128 v[202:205], v153 offset:4096
	ds_read_b128 v[206:209], v153 offset:5120
	ds_read_b128 v[210:213], v153 offset:6144
	ds_read_b128 v[214:217], v153 offset:7168
	global_load_lds_dwordx4 v[148:149], off
	v_lshl_add_u64 v[148:149], s[34:35], 0, v[142:143]
	s_add_i32 m0, s31, 0xe000
	s_nop 0
	global_load_lds_dwordx4 v[148:149], off
	s_waitcnt vmcnt(8)
	s_waitcnt lgkmcnt(0)
	s_barrier
	s_nop 0
	s_setprio 1
	s_waitcnt lgkmcnt(0)
	v_mfma_f32_16x16x32_bf16 v[126:129], v[154:157], v[186:189], v[126:129]
	v_mfma_f32_16x16x32_bf16 v[122:125], v[162:165], v[186:189], v[122:125]
	v_mfma_f32_16x16x32_bf16 v[114:117], v[154:157], v[194:197], v[114:117]
	v_mfma_f32_16x16x32_bf16 v[106:109], v[162:165], v[194:197], v[106:109]
	v_mfma_f32_16x16x32_bf16 v[98:101], v[154:157], v[202:205], v[98:101]
	v_mfma_f32_16x16x32_bf16 v[90:93], v[162:165], v[202:205], v[90:93]
	v_mfma_f32_16x16x32_bf16 v[82:85], v[154:157], v[210:213], v[82:85]
	v_mfma_f32_16x16x32_bf16 v[74:77], v[162:165], v[210:213], v[74:77]
	v_mfma_f32_16x16x32_bf16 v[126:129], v[158:161], v[190:193], v[126:129]
	v_mfma_f32_16x16x32_bf16 v[122:125], v[166:169], v[190:193], v[122:125]
	v_mfma_f32_16x16x32_bf16 v[114:117], v[158:161], v[198:201], v[114:117]
	v_mfma_f32_16x16x32_bf16 v[106:109], v[166:169], v[198:201], v[106:109]
	v_mfma_f32_16x16x32_bf16 v[98:101], v[158:161], v[206:209], v[98:101]
	v_mfma_f32_16x16x32_bf16 v[90:93], v[166:169], v[206:209], v[90:93]
	v_mfma_f32_16x16x32_bf16 v[82:85], v[158:161], v[214:217], v[82:85]
	v_mfma_f32_16x16x32_bf16 v[74:77], v[166:169], v[214:217], v[74:77]
	s_setprio 0
	s_setprio 1
	v_mfma_f32_16x16x32_bf16 v[118:121], v[170:173], v[186:189], v[118:121]
	v_mfma_f32_16x16x32_bf16 v[110:113], v[178:181], v[186:189], v[110:113]
	v_mfma_f32_16x16x32_bf16 v[102:105], v[170:173], v[194:197], v[102:105]
	v_mfma_f32_16x16x32_bf16 v[94:97], v[178:181], v[194:197], v[94:97]
	v_mfma_f32_16x16x32_bf16 v[86:89], v[170:173], v[202:205], v[86:89]
	v_mfma_f32_16x16x32_bf16 v[78:81], v[178:181], v[202:205], v[78:81]
	v_mfma_f32_16x16x32_bf16 v[70:73], v[170:173], v[210:213], v[70:73]
	v_mfma_f32_16x16x32_bf16 v[66:69], v[178:181], v[210:213], v[66:69]
	v_mfma_f32_16x16x32_bf16 v[118:121], v[174:177], v[190:193], v[118:121]
	v_mfma_f32_16x16x32_bf16 v[110:113], v[182:185], v[190:193], v[110:113]
	v_mfma_f32_16x16x32_bf16 v[102:105], v[174:177], v[198:201], v[102:105]
	v_mfma_f32_16x16x32_bf16 v[94:97], v[182:185], v[198:201], v[94:97]
	v_mfma_f32_16x16x32_bf16 v[86:89], v[174:177], v[206:209], v[86:89]
	v_mfma_f32_16x16x32_bf16 v[78:81], v[182:185], v[206:209], v[78:81]
	v_mfma_f32_16x16x32_bf16 v[70:73], v[174:177], v[214:217], v[70:73]
	v_mfma_f32_16x16x32_bf16 v[66:69], v[182:185], v[214:217], v[66:69]
	s_setprio 0
	s_barrier
	s_add_i32 s69, s54, s47
	v_lshl_add_u64 v[148:149], s[36:37], 0, v[136:137]
	s_mov_b32 m0, s69
	ds_read_b128 v[186:189], v153 offset:16384
	ds_read_b128 v[190:193], v153 offset:17408
	ds_read_b128 v[194:197], v153 offset:18432
	ds_read_b128 v[198:201], v153 offset:19456
	ds_read_b128 v[202:205], v153 offset:20480
	ds_read_b128 v[206:209], v153 offset:21504
	ds_read_b128 v[210:213], v153 offset:22528
	ds_read_b128 v[214:217], v153 offset:23552
	global_load_lds_dwordx4 v[148:149], off
	s_add_i32 m0, s69, 0x2000
	s_add_u32 s70, s36, 0x100000
	v_lshl_add_u64 v[218:219], s[36:37], 0, v[132:133]
	s_addc_u32 s71, s37, 0
	s_add_i32 s69, s55, s47
	global_load_lds_dwordx4 v[218:219], off
	v_lshl_add_u64 v[220:221], s[70:71], 0, v[136:137]
	s_mov_b32 m0, s69
	v_lshl_add_u64 v[222:223], s[38:39], 0, v[134:135]
	global_load_lds_dwordx4 v[220:221], off
	v_lshl_add_u64 v[220:221], s[70:71], 0, v[132:133]
	s_add_i32 m0, s69, 0x2000
	s_nop 0
	global_load_lds_dwordx4 v[220:221], off
	v_lshl_add_u64 v[220:221], s[38:39], 0, v[138:139]
	s_mov_b32 m0, s31
	s_nop 0
	global_load_lds_dwordx4 v[220:221], off
	s_mov_b32 m0, s48
	s_nop 0
	global_load_lds_dwordx4 v[222:223], off
	s_waitcnt vmcnt(8)
	s_waitcnt lgkmcnt(0)
	s_barrier
	s_nop 0
	s_setprio 1
	s_waitcnt lgkmcnt(0)
	v_mfma_f32_16x16x32_bf16 v[62:65], v[154:157], v[186:189], v[62:65]
	v_mfma_f32_16x16x32_bf16 v[58:61], v[162:165], v[186:189], v[58:61]
	v_mfma_f32_16x16x32_bf16 v[50:53], v[154:157], v[194:197], v[50:53]
	v_mfma_f32_16x16x32_bf16 v[42:45], v[162:165], v[194:197], v[42:45]
	v_mfma_f32_16x16x32_bf16 v[34:37], v[154:157], v[202:205], v[34:37]
	v_mfma_f32_16x16x32_bf16 v[26:29], v[162:165], v[202:205], v[26:29]
	v_mfma_f32_16x16x32_bf16 v[18:21], v[154:157], v[210:213], v[18:21]
	v_mfma_f32_16x16x32_bf16 v[10:13], v[162:165], v[210:213], v[10:13]
	v_mfma_f32_16x16x32_bf16 v[62:65], v[158:161], v[190:193], v[62:65]
	v_mfma_f32_16x16x32_bf16 v[58:61], v[166:169], v[190:193], v[58:61]
	v_mfma_f32_16x16x32_bf16 v[50:53], v[158:161], v[198:201], v[50:53]
	v_mfma_f32_16x16x32_bf16 v[42:45], v[166:169], v[198:201], v[42:45]
	v_mfma_f32_16x16x32_bf16 v[34:37], v[158:161], v[206:209], v[34:37]
	v_mfma_f32_16x16x32_bf16 v[26:29], v[166:169], v[206:209], v[26:29]
	v_mfma_f32_16x16x32_bf16 v[18:21], v[158:161], v[214:217], v[18:21]
	v_mfma_f32_16x16x32_bf16 v[10:13], v[166:169], v[214:217], v[10:13]
	s_setprio 0
	s_setprio 1
	v_mfma_f32_16x16x32_bf16 v[54:57], v[170:173], v[186:189], v[54:57]
	v_mfma_f32_16x16x32_bf16 v[46:49], v[178:181], v[186:189], v[46:49]
	v_mfma_f32_16x16x32_bf16 v[38:41], v[170:173], v[194:197], v[38:41]
	v_mfma_f32_16x16x32_bf16 v[30:33], v[178:181], v[194:197], v[30:33]
	v_mfma_f32_16x16x32_bf16 v[22:25], v[170:173], v[202:205], v[22:25]
	v_mfma_f32_16x16x32_bf16 v[14:17], v[178:181], v[202:205], v[14:17]
	v_mfma_f32_16x16x32_bf16 v[6:9], v[170:173], v[210:213], v[6:9]
	v_mfma_f32_16x16x32_bf16 v[2:5], v[178:181], v[210:213], v[2:5]
	v_mfma_f32_16x16x32_bf16 v[54:57], v[174:177], v[190:193], v[54:57]
	v_mfma_f32_16x16x32_bf16 v[46:49], v[182:185], v[190:193], v[46:49]
	v_mfma_f32_16x16x32_bf16 v[38:41], v[174:177], v[198:201], v[38:41]
	v_mfma_f32_16x16x32_bf16 v[30:33], v[182:185], v[198:201], v[30:33]
	v_mfma_f32_16x16x32_bf16 v[22:25], v[174:177], v[206:209], v[22:25]
	v_mfma_f32_16x16x32_bf16 v[14:17], v[182:185], v[206:209], v[14:17]
	v_mfma_f32_16x16x32_bf16 v[6:9], v[174:177], v[214:217], v[6:9]
	v_mfma_f32_16x16x32_bf16 v[2:5], v[182:185], v[214:217], v[2:5]
	s_setprio 0
	s_barrier
	s_add_i32 s69, 0, 0x18000
	s_add_i32 s70, 0, 0x1c000
	v_add_u32_e32 v166, s69, v131
	v_add_u32_e32 v182, s70, v131
	ds_read_b128 v[154:157], v166
	ds_read_b128 v[158:161], v166 offset:1024
	ds_read_b128 v[162:165], v166 offset:2048
	ds_read_b128 v[166:169], v166 offset:3072
	ds_read_b128 v[170:173], v182
	ds_read_b128 v[174:177], v182 offset:1024
	ds_read_b128 v[178:181], v182 offset:2048
	ds_read_b128 v[182:185], v182 offset:3072
	s_add_u32 s38, s38, 0x100000
	s_addc_u32 s39, s39, 0
	s_mov_b32 m0, s49
	v_lshl_add_u64 v[224:225], s[38:39], 0, v[138:139]
	ds_read_b128 v[186:189], v153 offset:32768
	ds_read_b128 v[190:193], v153 offset:33792
	ds_read_b128 v[194:197], v153 offset:34816
	ds_read_b128 v[198:201], v153 offset:35840
	ds_read_b128 v[202:205], v153 offset:36864
	ds_read_b128 v[206:209], v153 offset:37888
	ds_read_b128 v[210:213], v153 offset:38912
	ds_read_b128 v[214:217], v153 offset:39936
	global_load_lds_dwordx4 v[224:225], off
	v_lshl_add_u64 v[224:225], s[38:39], 0, v[134:135]
	s_mov_b32 m0, s50
	s_nop 0
	global_load_lds_dwordx4 v[224:225], off
	s_waitcnt vmcnt(8)
	s_waitcnt lgkmcnt(0)
	s_barrier
	s_nop 0
	s_setprio 1
	s_waitcnt lgkmcnt(0)
	v_mfma_f32_16x16x32_bf16 v[126:129], v[154:157], v[186:189], v[126:129]
	v_mfma_f32_16x16x32_bf16 v[122:125], v[162:165], v[186:189], v[122:125]
	v_mfma_f32_16x16x32_bf16 v[114:117], v[154:157], v[194:197], v[114:117]
	v_mfma_f32_16x16x32_bf16 v[106:109], v[162:165], v[194:197], v[106:109]
	v_mfma_f32_16x16x32_bf16 v[98:101], v[154:157], v[202:205], v[98:101]
	v_mfma_f32_16x16x32_bf16 v[90:93], v[162:165], v[202:205], v[90:93]
	v_mfma_f32_16x16x32_bf16 v[82:85], v[154:157], v[210:213], v[82:85]
	v_mfma_f32_16x16x32_bf16 v[74:77], v[162:165], v[210:213], v[74:77]
	v_mfma_f32_16x16x32_bf16 v[126:129], v[158:161], v[190:193], v[126:129]
	v_mfma_f32_16x16x32_bf16 v[122:125], v[166:169], v[190:193], v[122:125]
	v_mfma_f32_16x16x32_bf16 v[114:117], v[158:161], v[198:201], v[114:117]
	v_mfma_f32_16x16x32_bf16 v[106:109], v[166:169], v[198:201], v[106:109]
	v_mfma_f32_16x16x32_bf16 v[98:101], v[158:161], v[206:209], v[98:101]
	v_mfma_f32_16x16x32_bf16 v[90:93], v[166:169], v[206:209], v[90:93]
	v_mfma_f32_16x16x32_bf16 v[82:85], v[158:161], v[214:217], v[82:85]
	v_mfma_f32_16x16x32_bf16 v[74:77], v[166:169], v[214:217], v[74:77]
	s_setprio 0
	s_setprio 1
	v_mfma_f32_16x16x32_bf16 v[118:121], v[170:173], v[186:189], v[118:121]
	v_mfma_f32_16x16x32_bf16 v[110:113], v[178:181], v[186:189], v[110:113]
	v_mfma_f32_16x16x32_bf16 v[102:105], v[170:173], v[194:197], v[102:105]
	v_mfma_f32_16x16x32_bf16 v[94:97], v[178:181], v[194:197], v[94:97]
	v_mfma_f32_16x16x32_bf16 v[86:89], v[170:173], v[202:205], v[86:89]
	v_mfma_f32_16x16x32_bf16 v[78:81], v[178:181], v[202:205], v[78:81]
	v_mfma_f32_16x16x32_bf16 v[70:73], v[170:173], v[210:213], v[70:73]
	v_mfma_f32_16x16x32_bf16 v[66:69], v[178:181], v[210:213], v[66:69]
	v_mfma_f32_16x16x32_bf16 v[118:121], v[174:177], v[190:193], v[118:121]
	v_mfma_f32_16x16x32_bf16 v[110:113], v[182:185], v[190:193], v[110:113]
	v_mfma_f32_16x16x32_bf16 v[102:105], v[174:177], v[198:201], v[102:105]
	v_mfma_f32_16x16x32_bf16 v[94:97], v[182:185], v[198:201], v[94:97]
	v_mfma_f32_16x16x32_bf16 v[86:89], v[174:177], v[206:209], v[86:89]
	v_mfma_f32_16x16x32_bf16 v[78:81], v[182:185], v[206:209], v[78:81]
	v_mfma_f32_16x16x32_bf16 v[70:73], v[174:177], v[214:217], v[70:73]
	v_mfma_f32_16x16x32_bf16 v[66:69], v[182:185], v[214:217], v[66:69]
	s_setprio 0
	s_barrier
	s_add_i32 s38, s69, s47
	v_lshl_add_u64 v[148:149], v[148:149], 0, s[8:9]
	s_mov_b32 m0, s38
	ds_read_b128 v[186:189], v153 offset:49152
	ds_read_b128 v[190:193], v153 offset:50176
	ds_read_b128 v[194:197], v153 offset:51200
	ds_read_b128 v[198:201], v153 offset:52224
	ds_read_b128 v[202:205], v153 offset:53248
	ds_read_b128 v[206:209], v153 offset:54272
	ds_read_b128 v[210:213], v153 offset:55296
	ds_read_b128 v[214:217], v153 offset:56320
	global_load_lds_dwordx4 v[148:149], off
	s_add_i32 m0, s38, 0x2000
	s_add_u32 s36, s36, 0x100080
	v_lshl_add_u64 v[148:149], v[218:219], 0, s[8:9]
	s_addc_u32 s37, s37, 0
	s_add_i32 s38, s70, s47
	global_load_lds_dwordx4 v[148:149], off
	v_lshl_add_u64 v[148:149], s[36:37], 0, v[136:137]
	s_mov_b32 m0, s38
	s_nop 0
	global_load_lds_dwordx4 v[148:149], off
	v_lshl_add_u64 v[148:149], s[36:37], 0, v[132:133]
	s_add_i32 m0, s38, 0x2000
	s_nop 0
	global_load_lds_dwordx4 v[148:149], off
	v_lshl_add_u64 v[148:149], v[220:221], 0, s[8:9]
	s_mov_b32 m0, s52
	s_nop 0
	global_load_lds_dwordx4 v[148:149], off
	v_lshl_add_u64 v[148:149], v[222:223], 0, s[8:9]
	s_mov_b32 m0, s53
	s_nop 0
	global_load_lds_dwordx4 v[148:149], off
	s_waitcnt vmcnt(8)
	s_waitcnt lgkmcnt(0)
	s_barrier
	s_setprio 1
	s_waitcnt lgkmcnt(0)
	v_mfma_f32_16x16x32_bf16 v[62:65], v[154:157], v[186:189], v[62:65]
	v_mfma_f32_16x16x32_bf16 v[58:61], v[162:165], v[186:189], v[58:61]
	v_mfma_f32_16x16x32_bf16 v[50:53], v[154:157], v[194:197], v[50:53]
	v_mfma_f32_16x16x32_bf16 v[42:45], v[162:165], v[194:197], v[42:45]
	v_mfma_f32_16x16x32_bf16 v[34:37], v[154:157], v[202:205], v[34:37]
	v_mfma_f32_16x16x32_bf16 v[26:29], v[162:165], v[202:205], v[26:29]
	v_mfma_f32_16x16x32_bf16 v[18:21], v[154:157], v[210:213], v[18:21]
	v_mfma_f32_16x16x32_bf16 v[10:13], v[162:165], v[210:213], v[10:13]
	v_mfma_f32_16x16x32_bf16 v[62:65], v[158:161], v[190:193], v[62:65]
	v_mfma_f32_16x16x32_bf16 v[58:61], v[166:169], v[190:193], v[58:61]
	v_mfma_f32_16x16x32_bf16 v[50:53], v[158:161], v[198:201], v[50:53]
	v_mfma_f32_16x16x32_bf16 v[42:45], v[166:169], v[198:201], v[42:45]
	v_mfma_f32_16x16x32_bf16 v[34:37], v[158:161], v[206:209], v[34:37]
	v_mfma_f32_16x16x32_bf16 v[26:29], v[166:169], v[206:209], v[26:29]
	v_mfma_f32_16x16x32_bf16 v[18:21], v[158:161], v[214:217], v[18:21]
	v_mfma_f32_16x16x32_bf16 v[10:13], v[166:169], v[214:217], v[10:13]
	s_setprio 0
	s_setprio 1
	v_mfma_f32_16x16x32_bf16 v[54:57], v[170:173], v[186:189], v[54:57]
	v_mfma_f32_16x16x32_bf16 v[46:49], v[178:181], v[186:189], v[46:49]
	v_mfma_f32_16x16x32_bf16 v[38:41], v[170:173], v[194:197], v[38:41]
	v_mfma_f32_16x16x32_bf16 v[30:33], v[178:181], v[194:197], v[30:33]
	v_mfma_f32_16x16x32_bf16 v[22:25], v[170:173], v[202:205], v[22:25]
	v_mfma_f32_16x16x32_bf16 v[14:17], v[178:181], v[202:205], v[14:17]
	v_mfma_f32_16x16x32_bf16 v[6:9], v[170:173], v[210:213], v[6:9]
	v_mfma_f32_16x16x32_bf16 v[2:5], v[178:181], v[210:213], v[2:5]
	v_mfma_f32_16x16x32_bf16 v[54:57], v[174:177], v[190:193], v[54:57]
	v_mfma_f32_16x16x32_bf16 v[46:49], v[182:185], v[190:193], v[46:49]
	v_mfma_f32_16x16x32_bf16 v[38:41], v[174:177], v[198:201], v[38:41]
	v_mfma_f32_16x16x32_bf16 v[30:33], v[182:185], v[198:201], v[30:33]
	v_mfma_f32_16x16x32_bf16 v[22:25], v[174:177], v[206:209], v[22:25]
	v_mfma_f32_16x16x32_bf16 v[14:17], v[182:185], v[206:209], v[14:17]
	v_mfma_f32_16x16x32_bf16 v[6:9], v[174:177], v[214:217], v[6:9]
	v_mfma_f32_16x16x32_bf16 v[2:5], v[182:185], v[214:217], v[2:5]
	s_setprio 0
	s_barrier
	s_add_i32 s68, s68, 2
	s_add_u32 s34, s34, 0x100
	s_addc_u32 s35, s35, 0
	s_add_u32 s63, s63, 0x100
	s_addc_u32 s65, s65, 0
	s_cmp_gt_u32 s68, 61
	s_cbranch_scc0 .LBB0_668
	s_and_b64 vcc, exec, s[12:13]
	s_cbranch_vccz .LBB0_671
	s_barrier

.LBB0_845:
	ds_read_b128 v[130:133], v238
	ds_read_b128 v[134:137], v238 offset:1024
	ds_read_b128 v[138:141], v238 offset:2048
	ds_read_b128 v[142:145], v238 offset:3072
	ds_read_b128 v[146:149], v239
	ds_read_b128 v[150:153], v239 offset:1024
	ds_read_b128 v[154:157], v239 offset:2048
	ds_read_b128 v[158:161], v239 offset:3072
	s_add_u32 s56, s2, 0x100
	s_addc_u32 s57, s3, 0
	s_cmp_eq_u32 s92, 28
	s_cselect_b32 s61, s49, s57
	s_cselect_b32 s60, s88, s56
	s_cselect_b32 s59, s47, s91
	s_cselect_b32 s58, s89, s90
	v_lshl_add_u64 v[194:195], s[2:3], 0, v[210:211]
	s_add_i32 m0, s55, 0xc000
	ds_read_b128 v[162:165], v240
	ds_read_b128 v[166:169], v240 offset:1024
	ds_read_b128 v[170:173], v240 offset:2048
	ds_read_b128 v[174:177], v240 offset:3072
	ds_read_b128 v[178:181], v240 offset:4096
	ds_read_b128 v[182:185], v240 offset:5120
	ds_read_b128 v[186:189], v240 offset:6144
	ds_read_b128 v[190:193], v240 offset:7168
	global_load_lds_dwordx4 v[194:195], off
	v_lshl_add_u64 v[194:195], s[2:3], 0, v[212:213]
	s_add_i32 m0, s55, 0xe000
	s_nop 0
	global_load_lds_dwordx4 v[194:195], off
	s_waitcnt vmcnt(8)
	s_waitcnt lgkmcnt(0)
	s_barrier
	s_setprio 1
	s_waitcnt lgkmcnt(0)
	v_mfma_i32_16x16x64_i8 v[126:129], v[130:133], v[162:165], v[126:129]
	v_mfma_i32_16x16x64_i8 v[122:125], v[138:141], v[162:165], v[122:125]
	v_mfma_i32_16x16x64_i8 v[118:121], v[130:133], v[170:173], v[118:121]
	v_mfma_i32_16x16x64_i8 v[110:113], v[138:141], v[170:173], v[110:113]
	v_mfma_i32_16x16x64_i8 v[78:81], v[130:133], v[178:181], v[78:81]
	v_mfma_i32_16x16x64_i8 v[30:33], v[138:141], v[178:181], v[30:33]
	v_mfma_i32_16x16x64_i8 v[74:77], v[130:133], v[186:189], v[74:77]
	v_mfma_i32_16x16x64_i8 v[26:29], v[138:141], v[186:189], v[26:29]
	v_mfma_i32_16x16x64_i8 v[126:129], v[134:137], v[166:169], v[126:129]
	v_mfma_i32_16x16x64_i8 v[122:125], v[142:145], v[166:169], v[122:125]
	v_mfma_i32_16x16x64_i8 v[118:121], v[134:137], v[174:177], v[118:121]
	v_mfma_i32_16x16x64_i8 v[110:113], v[142:145], v[174:177], v[110:113]
	v_mfma_i32_16x16x64_i8 v[78:81], v[134:137], v[182:185], v[78:81]
	v_mfma_i32_16x16x64_i8 v[30:33], v[142:145], v[182:185], v[30:33]
	v_mfma_i32_16x16x64_i8 v[74:77], v[134:137], v[190:193], v[74:77]
	v_mfma_i32_16x16x64_i8 v[26:29], v[142:145], v[190:193], v[26:29]
	s_setprio 0
	s_setprio 1
	v_mfma_i32_16x16x64_i8 v[102:105], v[146:149], v[162:165], v[102:105]
	v_mfma_i32_16x16x64_i8 v[98:101], v[154:157], v[162:165], v[98:101]
	v_mfma_i32_16x16x64_i8 v[94:97], v[146:149], v[170:173], v[94:97]
	v_mfma_i32_16x16x64_i8 v[90:93], v[154:157], v[170:173], v[90:93]
	v_mfma_i32_16x16x64_i8 v[70:73], v[146:149], v[178:181], v[70:73]
	v_mfma_i32_16x16x64_i8 v[22:25], v[154:157], v[178:181], v[22:25]
	v_mfma_i32_16x16x64_i8 v[66:69], v[146:149], v[186:189], v[66:69]
	v_mfma_i32_16x16x64_i8 v[18:21], v[154:157], v[186:189], v[18:21]
	v_mfma_i32_16x16x64_i8 v[102:105], v[150:153], v[166:169], v[102:105]
	v_mfma_i32_16x16x64_i8 v[98:101], v[158:161], v[166:169], v[98:101]
	v_mfma_i32_16x16x64_i8 v[94:97], v[150:153], v[174:177], v[94:97]
	v_mfma_i32_16x16x64_i8 v[90:93], v[158:161], v[174:177], v[90:93]
	v_mfma_i32_16x16x64_i8 v[70:73], v[150:153], v[182:185], v[70:73]
	v_mfma_i32_16x16x64_i8 v[22:25], v[158:161], v[182:185], v[22:25]
	v_mfma_i32_16x16x64_i8 v[66:69], v[150:153], v[190:193], v[66:69]
	v_mfma_i32_16x16x64_i8 v[18:21], v[158:161], v[190:193], v[18:21]
	s_setprio 0
	s_barrier
	s_add_i32 s2, s84, s65
	v_lshl_add_u64 v[194:195], s[58:59], 0, v[206:207]
	s_mov_b32 m0, s2
	ds_read_b128 v[162:165], v240 offset:16384
	ds_read_b128 v[166:169], v240 offset:17408
	ds_read_b128 v[170:173], v240 offset:18432
	ds_read_b128 v[174:177], v240 offset:19456
	ds_read_b128 v[178:181], v240 offset:20480
	ds_read_b128 v[182:185], v240 offset:21504
	ds_read_b128 v[186:189], v240 offset:22528
	ds_read_b128 v[190:193], v240 offset:23552
	global_load_lds_dwordx4 v[194:195], off
	s_add_i32 m0, s2, 0x2000
	s_add_u32 s2, s58, 0x80000
	v_lshl_add_u64 v[196:197], s[58:59], 0, v[202:203]
	s_addc_u32 s3, s59, 0
	s_add_i32 s93, s85, s65
	global_load_lds_dwordx4 v[196:197], off
	v_lshl_add_u64 v[198:199], s[2:3], 0, v[206:207]
	s_mov_b32 m0, s93
	v_lshl_add_u64 v[200:201], s[60:61], 0, v[204:205]
	global_load_lds_dwordx4 v[198:199], off
	v_lshl_add_u64 v[198:199], s[2:3], 0, v[202:203]
	s_add_i32 m0, s93, 0x2000
	s_nop 0
	global_load_lds_dwordx4 v[198:199], off
	v_lshl_add_u64 v[198:199], s[60:61], 0, v[208:209]
	s_mov_b32 m0, s55
	s_nop 0
	global_load_lds_dwordx4 v[198:199], off
	s_mov_b32 m0, s69
	s_nop 0
	global_load_lds_dwordx4 v[200:201], off
	s_waitcnt vmcnt(8)
	s_waitcnt lgkmcnt(0)
	s_barrier
	s_nop 0
	s_setprio 1
	s_waitcnt lgkmcnt(0)
	v_mfma_i32_16x16x64_i8 v[62:65], v[130:133], v[162:165], v[62:65]
	v_mfma_i32_16x16x64_i8 v[14:17], v[138:141], v[162:165], v[14:17]
	v_mfma_i32_16x16x64_i8 v[58:61], v[130:133], v[170:173], v[58:61]
	v_mfma_i32_16x16x64_i8 v[10:13], v[138:141], v[170:173], v[10:13]
	v_mfma_i32_16x16x64_i8 v[114:117], v[130:133], v[178:181], v[114:117]
	v_mfma_i32_16x16x64_i8 v[106:109], v[138:141], v[178:181], v[106:109]
	v_mfma_i32_16x16x64_i8 v[86:89], v[130:133], v[186:189], v[86:89]
	v_mfma_i32_16x16x64_i8 v[82:85], v[138:141], v[186:189], v[82:85]
	v_mfma_i32_16x16x64_i8 v[62:65], v[134:137], v[166:169], v[62:65]
	v_mfma_i32_16x16x64_i8 v[14:17], v[142:145], v[166:169], v[14:17]
	v_mfma_i32_16x16x64_i8 v[58:61], v[134:137], v[174:177], v[58:61]
	v_mfma_i32_16x16x64_i8 v[10:13], v[142:145], v[174:177], v[10:13]
	v_mfma_i32_16x16x64_i8 v[114:117], v[134:137], v[182:185], v[114:117]
	v_mfma_i32_16x16x64_i8 v[106:109], v[142:145], v[182:185], v[106:109]
	v_mfma_i32_16x16x64_i8 v[86:89], v[134:137], v[190:193], v[86:89]
	v_mfma_i32_16x16x64_i8 v[82:85], v[142:145], v[190:193], v[82:85]
	s_setprio 0
	s_setprio 1
	v_mfma_i32_16x16x64_i8 v[50:53], v[146:149], v[162:165], v[50:53]
	v_mfma_i32_16x16x64_i8 v[6:9], v[154:157], v[162:165], v[6:9]
	v_mfma_i32_16x16x64_i8 v[42:45], v[146:149], v[170:173], v[42:45]
	v_mfma_i32_16x16x64_i8 v[2:5], v[154:157], v[170:173], v[2:5]
	v_mfma_i32_16x16x64_i8 v[54:57], v[146:149], v[178:181], v[54:57]
	v_mfma_i32_16x16x64_i8 v[46:49], v[154:157], v[178:181], v[46:49]
	v_mfma_i32_16x16x64_i8 v[38:41], v[146:149], v[186:189], v[38:41]
	v_mfma_i32_16x16x64_i8 v[34:37], v[154:157], v[186:189], v[34:37]
	v_mfma_i32_16x16x64_i8 v[50:53], v[150:153], v[166:169], v[50:53]
	v_mfma_i32_16x16x64_i8 v[6:9], v[158:161], v[166:169], v[6:9]
	v_mfma_i32_16x16x64_i8 v[42:45], v[150:153], v[174:177], v[42:45]
	v_mfma_i32_16x16x64_i8 v[2:5], v[158:161], v[174:177], v[2:5]
	v_mfma_i32_16x16x64_i8 v[54:57], v[150:153], v[182:185], v[54:57]
	v_mfma_i32_16x16x64_i8 v[46:49], v[158:161], v[182:185], v[46:49]
	v_mfma_i32_16x16x64_i8 v[38:41], v[150:153], v[190:193], v[38:41]
	v_mfma_i32_16x16x64_i8 v[34:37], v[158:161], v[190:193], v[34:37]
	s_setprio 0
	s_barrier
	s_add_i32 s93, 0, 0x18000
	s_add_i32 s94, 0, 0x1c000
	v_add_u32_e32 v142, s93, v237
	v_add_u32_e32 v158, s94, v237
	ds_read_b128 v[130:133], v142
	ds_read_b128 v[134:137], v142 offset:1024
	ds_read_b128 v[138:141], v142 offset:2048
	ds_read_b128 v[142:145], v142 offset:3072
	ds_read_b128 v[146:149], v158
	ds_read_b128 v[150:153], v158 offset:1024
	ds_read_b128 v[154:157], v158 offset:2048
	ds_read_b128 v[158:161], v158 offset:3072
	s_add_u32 s2, s60, 0x4000
	s_addc_u32 s3, s61, 0
	s_mov_b32 m0, s70
	v_lshl_add_u64 v[220:221], s[2:3], 0, v[208:209]
	ds_read_b128 v[162:165], v240 offset:32768
	ds_read_b128 v[166:169], v240 offset:33792
	ds_read_b128 v[170:173], v240 offset:34816
	ds_read_b128 v[174:177], v240 offset:35840
	ds_read_b128 v[178:181], v240 offset:36864
	ds_read_b128 v[182:185], v240 offset:37888
	ds_read_b128 v[186:189], v240 offset:38912
	ds_read_b128 v[190:193], v240 offset:39936
	global_load_lds_dwordx4 v[220:221], off
	v_lshl_add_u64 v[220:221], s[2:3], 0, v[204:205]
	s_mov_b32 m0, s71
	s_nop 0
	global_load_lds_dwordx4 v[220:221], off
	s_waitcnt vmcnt(8)
	s_waitcnt lgkmcnt(0)
	s_barrier
	s_nop 0
	s_setprio 1
	s_waitcnt lgkmcnt(0)
	v_mfma_i32_16x16x64_i8 v[126:129], v[130:133], v[162:165], v[126:129]
	v_mfma_i32_16x16x64_i8 v[122:125], v[138:141], v[162:165], v[122:125]
	v_mfma_i32_16x16x64_i8 v[118:121], v[130:133], v[170:173], v[118:121]
	v_mfma_i32_16x16x64_i8 v[110:113], v[138:141], v[170:173], v[110:113]
	v_mfma_i32_16x16x64_i8 v[78:81], v[130:133], v[178:181], v[78:81]
	v_mfma_i32_16x16x64_i8 v[30:33], v[138:141], v[178:181], v[30:33]
	v_mfma_i32_16x16x64_i8 v[74:77], v[130:133], v[186:189], v[74:77]
	v_mfma_i32_16x16x64_i8 v[26:29], v[138:141], v[186:189], v[26:29]
	v_mfma_i32_16x16x64_i8 v[126:129], v[134:137], v[166:169], v[126:129]
	v_mfma_i32_16x16x64_i8 v[122:125], v[142:145], v[166:169], v[122:125]
	v_mfma_i32_16x16x64_i8 v[118:121], v[134:137], v[174:177], v[118:121]
	v_mfma_i32_16x16x64_i8 v[110:113], v[142:145], v[174:177], v[110:113]
	v_mfma_i32_16x16x64_i8 v[78:81], v[134:137], v[182:185], v[78:81]
	v_mfma_i32_16x16x64_i8 v[30:33], v[142:145], v[182:185], v[30:33]
	v_mfma_i32_16x16x64_i8 v[74:77], v[134:137], v[190:193], v[74:77]
	v_mfma_i32_16x16x64_i8 v[26:29], v[142:145], v[190:193], v[26:29]
	s_setprio 0
	s_setprio 1
	v_mfma_i32_16x16x64_i8 v[102:105], v[146:149], v[162:165], v[102:105]
	v_mfma_i32_16x16x64_i8 v[98:101], v[154:157], v[162:165], v[98:101]
	v_mfma_i32_16x16x64_i8 v[94:97], v[146:149], v[170:173], v[94:97]
	v_mfma_i32_16x16x64_i8 v[90:93], v[154:157], v[170:173], v[90:93]
	v_mfma_i32_16x16x64_i8 v[70:73], v[146:149], v[178:181], v[70:73]
	v_mfma_i32_16x16x64_i8 v[22:25], v[154:157], v[178:181], v[22:25]
	v_mfma_i32_16x16x64_i8 v[66:69], v[146:149], v[186:189], v[66:69]
	v_mfma_i32_16x16x64_i8 v[18:21], v[154:157], v[186:189], v[18:21]
	v_mfma_i32_16x16x64_i8 v[102:105], v[150:153], v[166:169], v[102:105]
	v_mfma_i32_16x16x64_i8 v[98:101], v[158:161], v[166:169], v[98:101]
	v_mfma_i32_16x16x64_i8 v[94:97], v[150:153], v[174:177], v[94:97]
	v_mfma_i32_16x16x64_i8 v[90:93], v[158:161], v[174:177], v[90:93]
	v_mfma_i32_16x16x64_i8 v[70:73], v[150:153], v[182:185], v[70:73]
	v_mfma_i32_16x16x64_i8 v[22:25], v[158:161], v[182:185], v[22:25]
	v_mfma_i32_16x16x64_i8 v[66:69], v[150:153], v[190:193], v[66:69]
	v_mfma_i32_16x16x64_i8 v[18:21], v[158:161], v[190:193], v[18:21]
	s_setprio 0
	s_barrier
	s_add_i32 s2, s93, s65
	v_lshl_add_u64 v[194:195], v[194:195], 0, s[36:37]
	s_mov_b32 m0, s2
	ds_read_b128 v[162:165], v240 offset:49152
	ds_read_b128 v[166:169], v240 offset:50176
	ds_read_b128 v[170:173], v240 offset:51200
	ds_read_b128 v[174:177], v240 offset:52224
	ds_read_b128 v[178:181], v240 offset:53248
	ds_read_b128 v[182:185], v240 offset:54272
	ds_read_b128 v[186:189], v240 offset:55296
	ds_read_b128 v[190:193], v240 offset:56320
	global_load_lds_dwordx4 v[194:195], off
	s_add_i32 m0, s2, 0x2000
	s_add_u32 s2, s58, 0x80080
	v_lshl_add_u64 v[194:195], v[196:197], 0, s[36:37]
	s_addc_u32 s3, s59, 0
	s_add_i32 s58, s94, s65
	global_load_lds_dwordx4 v[194:195], off
	v_lshl_add_u64 v[194:195], s[2:3], 0, v[206:207]
	s_mov_b32 m0, s58
	s_nop 0
	global_load_lds_dwordx4 v[194:195], off
	v_lshl_add_u64 v[194:195], s[2:3], 0, v[202:203]
	s_add_i32 m0, s58, 0x2000
	s_nop 0
	global_load_lds_dwordx4 v[194:195], off
	v_lshl_add_u64 v[194:195], v[198:199], 0, s[36:37]
	s_mov_b32 m0, s78
	s_nop 0
	global_load_lds_dwordx4 v[194:195], off
	v_lshl_add_u64 v[194:195], v[200:201], 0, s[36:37]
	s_mov_b32 m0, s79
	s_nop 0
	global_load_lds_dwordx4 v[194:195], off
	s_waitcnt vmcnt(8)
	s_waitcnt lgkmcnt(0)
	s_barrier
	s_setprio 1
	s_waitcnt lgkmcnt(0)
	v_mfma_i32_16x16x64_i8 v[62:65], v[130:133], v[162:165], v[62:65]
	v_mfma_i32_16x16x64_i8 v[14:17], v[138:141], v[162:165], v[14:17]
	v_mfma_i32_16x16x64_i8 v[58:61], v[130:133], v[170:173], v[58:61]
	v_mfma_i32_16x16x64_i8 v[10:13], v[138:141], v[170:173], v[10:13]
	v_mfma_i32_16x16x64_i8 v[114:117], v[130:133], v[178:181], v[114:117]
	v_mfma_i32_16x16x64_i8 v[106:109], v[138:141], v[178:181], v[106:109]
	v_mfma_i32_16x16x64_i8 v[86:89], v[130:133], v[186:189], v[86:89]
	v_mfma_i32_16x16x64_i8 v[82:85], v[138:141], v[186:189], v[82:85]
	v_mfma_i32_16x16x64_i8 v[62:65], v[134:137], v[166:169], v[62:65]
	v_mfma_i32_16x16x64_i8 v[14:17], v[142:145], v[166:169], v[14:17]
	v_mfma_i32_16x16x64_i8 v[58:61], v[134:137], v[174:177], v[58:61]
	v_mfma_i32_16x16x64_i8 v[10:13], v[142:145], v[174:177], v[10:13]
	v_mfma_i32_16x16x64_i8 v[114:117], v[134:137], v[182:185], v[114:117]
	v_mfma_i32_16x16x64_i8 v[106:109], v[142:145], v[182:185], v[106:109]
	v_mfma_i32_16x16x64_i8 v[86:89], v[134:137], v[190:193], v[86:89]
	v_mfma_i32_16x16x64_i8 v[82:85], v[142:145], v[190:193], v[82:85]
	s_setprio 0
	s_setprio 1
	v_mfma_i32_16x16x64_i8 v[50:53], v[146:149], v[162:165], v[50:53]
	v_mfma_i32_16x16x64_i8 v[6:9], v[154:157], v[162:165], v[6:9]
	v_mfma_i32_16x16x64_i8 v[42:45], v[146:149], v[170:173], v[42:45]
	v_mfma_i32_16x16x64_i8 v[2:5], v[154:157], v[170:173], v[2:5]
	v_mfma_i32_16x16x64_i8 v[54:57], v[146:149], v[178:181], v[54:57]
	v_mfma_i32_16x16x64_i8 v[46:49], v[154:157], v[178:181], v[46:49]
	v_mfma_i32_16x16x64_i8 v[38:41], v[146:149], v[186:189], v[38:41]
	v_mfma_i32_16x16x64_i8 v[34:37], v[154:157], v[186:189], v[34:37]
	v_mfma_i32_16x16x64_i8 v[50:53], v[150:153], v[166:169], v[50:53]
	v_mfma_i32_16x16x64_i8 v[6:9], v[158:161], v[166:169], v[6:9]
	v_mfma_i32_16x16x64_i8 v[42:45], v[150:153], v[174:177], v[42:45]
	v_mfma_i32_16x16x64_i8 v[2:5], v[158:161], v[174:177], v[2:5]
	v_mfma_i32_16x16x64_i8 v[54:57], v[150:153], v[182:185], v[54:57]
	v_mfma_i32_16x16x64_i8 v[46:49], v[158:161], v[182:185], v[46:49]
	v_mfma_i32_16x16x64_i8 v[38:41], v[150:153], v[190:193], v[38:41]
	v_mfma_i32_16x16x64_i8 v[34:37], v[158:161], v[190:193], v[34:37]
	s_setprio 0
	s_barrier
	s_add_i32 s92, s92, 2
	s_add_u32 s90, s90, 0x100
	s_addc_u32 s91, s91, 0
	s_cmp_gt_u32 s92, 29
	s_mov_b64 s[2:3], s[56:57]
	s_cbranch_scc0 .LBB0_845
	s_and_b64 vcc, exec, s[38:39]
	s_cbranch_vccz .LBB0_848
	s_barrier

.LBB0_1099:
	ds_read_b128 v[130:133], v167
	ds_read_b128 v[134:137], v167 offset:1024
	ds_read_b128 v[138:141], v167 offset:2048
	ds_read_b128 v[142:145], v167 offset:3072
	ds_read_b128 v[170:173], v168
	ds_read_b128 v[174:177], v168 offset:1024
	ds_read_b128 v[178:181], v168 offset:2048
	ds_read_b128 v[182:185], v168 offset:3072
	s_add_u32 s30, s28, 0x100
	s_addc_u32 s31, s29, 0
	s_cmpk_eq_i32 s72, 0x52
	s_cselect_b32 s37, s3, s31
	s_cselect_b32 s36, s2, s30
	s_cselect_b32 s35, s27, s71
	s_cselect_b32 s34, s26, s70
	v_lshl_add_u64 v[162:163], s[28:29], 0, v[154:155]
	s_add_i32 m0, s47, 0xc000
	ds_read_b128 v[186:189], v169
	ds_read_b128 v[190:193], v169 offset:1024
	ds_read_b128 v[194:197], v169 offset:2048
	ds_read_b128 v[198:201], v169 offset:3072
	ds_read_b128 v[202:205], v169 offset:4096
	ds_read_b128 v[206:209], v169 offset:5120
	ds_read_b128 v[210:213], v169 offset:6144
	ds_read_b128 v[214:217], v169 offset:7168
	global_load_lds_dwordx4 v[162:163], off
	v_lshl_add_u64 v[162:163], s[28:29], 0, v[156:157]
	s_add_i32 m0, s47, 0xe000
	s_nop 0
	global_load_lds_dwordx4 v[162:163], off
	s_waitcnt vmcnt(8)
	s_waitcnt lgkmcnt(0)
	s_barrier
	s_nop 0
	s_setprio 1
	s_waitcnt lgkmcnt(0)
	v_mfma_i32_16x16x64_i8 v[126:129], v[130:133], v[186:189], v[126:129]
	v_mfma_i32_16x16x64_i8 v[122:125], v[138:141], v[186:189], v[122:125]
	v_mfma_i32_16x16x64_i8 v[110:113], v[130:133], v[194:197], v[110:113]
	v_mfma_i32_16x16x64_i8 v[106:109], v[138:141], v[194:197], v[106:109]
	v_mfma_i32_16x16x64_i8 v[94:97], v[130:133], v[202:205], v[94:97]
	v_mfma_i32_16x16x64_i8 v[90:93], v[138:141], v[202:205], v[90:93]
	v_mfma_i32_16x16x64_i8 v[78:81], v[130:133], v[210:213], v[78:81]
	v_mfma_i32_16x16x64_i8 v[74:77], v[138:141], v[210:213], v[74:77]
	v_mfma_i32_16x16x64_i8 v[126:129], v[134:137], v[190:193], v[126:129]
	v_mfma_i32_16x16x64_i8 v[122:125], v[142:145], v[190:193], v[122:125]
	v_mfma_i32_16x16x64_i8 v[110:113], v[134:137], v[198:201], v[110:113]
	v_mfma_i32_16x16x64_i8 v[106:109], v[142:145], v[198:201], v[106:109]
	v_mfma_i32_16x16x64_i8 v[94:97], v[134:137], v[206:209], v[94:97]
	v_mfma_i32_16x16x64_i8 v[90:93], v[142:145], v[206:209], v[90:93]
	v_mfma_i32_16x16x64_i8 v[78:81], v[134:137], v[214:217], v[78:81]
	v_mfma_i32_16x16x64_i8 v[74:77], v[142:145], v[214:217], v[74:77]
	s_setprio 0
	s_setprio 1
	v_mfma_i32_16x16x64_i8 v[118:121], v[170:173], v[186:189], v[118:121]
	v_mfma_i32_16x16x64_i8 v[114:117], v[178:181], v[186:189], v[114:117]
	v_mfma_i32_16x16x64_i8 v[102:105], v[170:173], v[194:197], v[102:105]
	v_mfma_i32_16x16x64_i8 v[98:101], v[178:181], v[194:197], v[98:101]
	v_mfma_i32_16x16x64_i8 v[86:89], v[170:173], v[202:205], v[86:89]
	v_mfma_i32_16x16x64_i8 v[82:85], v[178:181], v[202:205], v[82:85]
	v_mfma_i32_16x16x64_i8 v[70:73], v[170:173], v[210:213], v[70:73]
	v_mfma_i32_16x16x64_i8 v[66:69], v[178:181], v[210:213], v[66:69]
	v_mfma_i32_16x16x64_i8 v[118:121], v[174:177], v[190:193], v[118:121]
	v_mfma_i32_16x16x64_i8 v[114:117], v[182:185], v[190:193], v[114:117]
	v_mfma_i32_16x16x64_i8 v[102:105], v[174:177], v[198:201], v[102:105]
	v_mfma_i32_16x16x64_i8 v[98:101], v[182:185], v[198:201], v[98:101]
	v_mfma_i32_16x16x64_i8 v[86:89], v[174:177], v[206:209], v[86:89]
	v_mfma_i32_16x16x64_i8 v[82:85], v[182:185], v[206:209], v[82:85]
	v_mfma_i32_16x16x64_i8 v[70:73], v[174:177], v[214:217], v[70:73]
	v_mfma_i32_16x16x64_i8 v[66:69], v[182:185], v[214:217], v[66:69]
	s_setprio 0
	s_barrier
	s_add_i32 s28, s56, s46
	v_lshl_add_u64 v[162:163], s[34:35], 0, v[150:151]
	s_mov_b32 m0, s28
	ds_read_b128 v[186:189], v169 offset:16384
	ds_read_b128 v[190:193], v169 offset:17408
	ds_read_b128 v[194:197], v169 offset:18432
	ds_read_b128 v[198:201], v169 offset:19456
	ds_read_b128 v[202:205], v169 offset:20480
	ds_read_b128 v[206:209], v169 offset:21504
	ds_read_b128 v[210:213], v169 offset:22528
	ds_read_b128 v[214:217], v169 offset:23552
	global_load_lds_dwordx4 v[162:163], off
	s_add_i32 m0, s28, 0x2000
	s_add_u32 s28, s34, 0x158000
	v_lshl_add_u64 v[218:219], s[34:35], 0, v[146:147]
	s_addc_u32 s29, s35, 0
	s_add_i32 s73, s57, s46
	global_load_lds_dwordx4 v[218:219], off
	v_lshl_add_u64 v[220:221], s[28:29], 0, v[150:151]
	s_mov_b32 m0, s73
	v_lshl_add_u64 v[222:223], s[36:37], 0, v[148:149]
	global_load_lds_dwordx4 v[220:221], off
	v_lshl_add_u64 v[220:221], s[28:29], 0, v[146:147]
	s_add_i32 m0, s73, 0x2000
	s_nop 0
	global_load_lds_dwordx4 v[220:221], off
	v_lshl_add_u64 v[220:221], s[36:37], 0, v[152:153]
	s_mov_b32 m0, s47
	s_nop 0
	global_load_lds_dwordx4 v[220:221], off
	s_mov_b32 m0, s48
	s_nop 0
	global_load_lds_dwordx4 v[222:223], off
	s_waitcnt vmcnt(8)
	s_waitcnt lgkmcnt(0)
	s_barrier
	s_nop 0
	s_setprio 1
	s_waitcnt lgkmcnt(0)
	v_mfma_i32_16x16x64_i8 v[62:65], v[130:133], v[186:189], v[62:65]
	v_mfma_i32_16x16x64_i8 v[58:61], v[138:141], v[186:189], v[58:61]
	v_mfma_i32_16x16x64_i8 v[46:49], v[130:133], v[194:197], v[46:49]
	v_mfma_i32_16x16x64_i8 v[42:45], v[138:141], v[194:197], v[42:45]
	v_mfma_i32_16x16x64_i8 v[30:33], v[130:133], v[202:205], v[30:33]
	v_mfma_i32_16x16x64_i8 v[26:29], v[138:141], v[202:205], v[26:29]
	v_mfma_i32_16x16x64_i8 v[14:17], v[130:133], v[210:213], v[14:17]
	v_mfma_i32_16x16x64_i8 v[10:13], v[138:141], v[210:213], v[10:13]
	v_mfma_i32_16x16x64_i8 v[62:65], v[134:137], v[190:193], v[62:65]
	v_mfma_i32_16x16x64_i8 v[58:61], v[142:145], v[190:193], v[58:61]
	v_mfma_i32_16x16x64_i8 v[46:49], v[134:137], v[198:201], v[46:49]
	v_mfma_i32_16x16x64_i8 v[42:45], v[142:145], v[198:201], v[42:45]
	v_mfma_i32_16x16x64_i8 v[30:33], v[134:137], v[206:209], v[30:33]
	v_mfma_i32_16x16x64_i8 v[26:29], v[142:145], v[206:209], v[26:29]
	v_mfma_i32_16x16x64_i8 v[14:17], v[134:137], v[214:217], v[14:17]
	v_mfma_i32_16x16x64_i8 v[10:13], v[142:145], v[214:217], v[10:13]
	s_setprio 0
	s_setprio 1
	v_mfma_i32_16x16x64_i8 v[54:57], v[170:173], v[186:189], v[54:57]
	v_mfma_i32_16x16x64_i8 v[50:53], v[178:181], v[186:189], v[50:53]
	v_mfma_i32_16x16x64_i8 v[38:41], v[170:173], v[194:197], v[38:41]
	v_mfma_i32_16x16x64_i8 v[34:37], v[178:181], v[194:197], v[34:37]
	v_mfma_i32_16x16x64_i8 v[22:25], v[170:173], v[202:205], v[22:25]
	v_mfma_i32_16x16x64_i8 v[18:21], v[178:181], v[202:205], v[18:21]
	v_mfma_i32_16x16x64_i8 v[6:9], v[170:173], v[210:213], v[6:9]
	v_mfma_i32_16x16x64_i8 v[2:5], v[178:181], v[210:213], v[2:5]
	v_mfma_i32_16x16x64_i8 v[54:57], v[174:177], v[190:193], v[54:57]
	v_mfma_i32_16x16x64_i8 v[50:53], v[182:185], v[190:193], v[50:53]
	v_mfma_i32_16x16x64_i8 v[38:41], v[174:177], v[198:201], v[38:41]
	v_mfma_i32_16x16x64_i8 v[34:37], v[182:185], v[198:201], v[34:37]
	v_mfma_i32_16x16x64_i8 v[22:25], v[174:177], v[206:209], v[22:25]
	v_mfma_i32_16x16x64_i8 v[18:21], v[182:185], v[206:209], v[18:21]
	v_mfma_i32_16x16x64_i8 v[6:9], v[174:177], v[214:217], v[6:9]
	v_mfma_i32_16x16x64_i8 v[2:5], v[182:185], v[214:217], v[2:5]
	s_setprio 0
	s_barrier
	s_add_i32 s73, 0, 0x18000
	s_add_i32 s74, 0, 0x1c000
	v_add_u32_e32 v142, s73, v166
	v_add_u32_e32 v182, s74, v166
	ds_read_b128 v[130:133], v142
	ds_read_b128 v[134:137], v142 offset:1024
	ds_read_b128 v[138:141], v142 offset:2048
	ds_read_b128 v[142:145], v142 offset:3072
	ds_read_b128 v[170:173], v182
	ds_read_b128 v[174:177], v182 offset:1024
	ds_read_b128 v[178:181], v182 offset:2048
	ds_read_b128 v[182:185], v182 offset:3072
	s_add_u32 s28, s36, 0x158000
	s_addc_u32 s29, s37, 0
	s_mov_b32 m0, s49
	v_lshl_add_u64 v[224:225], s[28:29], 0, v[152:153]
	ds_read_b128 v[186:189], v169 offset:32768
	ds_read_b128 v[190:193], v169 offset:33792
	ds_read_b128 v[194:197], v169 offset:34816
	ds_read_b128 v[198:201], v169 offset:35840
	ds_read_b128 v[202:205], v169 offset:36864
	ds_read_b128 v[206:209], v169 offset:37888
	ds_read_b128 v[210:213], v169 offset:38912
	ds_read_b128 v[214:217], v169 offset:39936
	global_load_lds_dwordx4 v[224:225], off
	v_lshl_add_u64 v[224:225], s[28:29], 0, v[148:149]
	s_mov_b32 m0, s50
	s_nop 0
	global_load_lds_dwordx4 v[224:225], off
	s_waitcnt vmcnt(8)
	s_waitcnt lgkmcnt(0)
	s_barrier
	s_nop 0
	s_setprio 1
	s_waitcnt lgkmcnt(0)
	v_mfma_i32_16x16x64_i8 v[126:129], v[130:133], v[186:189], v[126:129]
	v_mfma_i32_16x16x64_i8 v[122:125], v[138:141], v[186:189], v[122:125]
	v_mfma_i32_16x16x64_i8 v[110:113], v[130:133], v[194:197], v[110:113]
	v_mfma_i32_16x16x64_i8 v[106:109], v[138:141], v[194:197], v[106:109]
	v_mfma_i32_16x16x64_i8 v[94:97], v[130:133], v[202:205], v[94:97]
	v_mfma_i32_16x16x64_i8 v[90:93], v[138:141], v[202:205], v[90:93]
	v_mfma_i32_16x16x64_i8 v[78:81], v[130:133], v[210:213], v[78:81]
	v_mfma_i32_16x16x64_i8 v[74:77], v[138:141], v[210:213], v[74:77]
	v_mfma_i32_16x16x64_i8 v[126:129], v[134:137], v[190:193], v[126:129]
	v_mfma_i32_16x16x64_i8 v[122:125], v[142:145], v[190:193], v[122:125]
	v_mfma_i32_16x16x64_i8 v[110:113], v[134:137], v[198:201], v[110:113]
	v_mfma_i32_16x16x64_i8 v[106:109], v[142:145], v[198:201], v[106:109]
	v_mfma_i32_16x16x64_i8 v[94:97], v[134:137], v[206:209], v[94:97]
	v_mfma_i32_16x16x64_i8 v[90:93], v[142:145], v[206:209], v[90:93]
	v_mfma_i32_16x16x64_i8 v[78:81], v[134:137], v[214:217], v[78:81]
	v_mfma_i32_16x16x64_i8 v[74:77], v[142:145], v[214:217], v[74:77]
	s_setprio 0
	s_setprio 1
	v_mfma_i32_16x16x64_i8 v[118:121], v[170:173], v[186:189], v[118:121]
	v_mfma_i32_16x16x64_i8 v[114:117], v[178:181], v[186:189], v[114:117]
	v_mfma_i32_16x16x64_i8 v[102:105], v[170:173], v[194:197], v[102:105]
	v_mfma_i32_16x16x64_i8 v[98:101], v[178:181], v[194:197], v[98:101]
	v_mfma_i32_16x16x64_i8 v[86:89], v[170:173], v[202:205], v[86:89]
	v_mfma_i32_16x16x64_i8 v[82:85], v[178:181], v[202:205], v[82:85]
	v_mfma_i32_16x16x64_i8 v[70:73], v[170:173], v[210:213], v[70:73]
	v_mfma_i32_16x16x64_i8 v[66:69], v[178:181], v[210:213], v[66:69]
	v_mfma_i32_16x16x64_i8 v[118:121], v[174:177], v[190:193], v[118:121]
	v_mfma_i32_16x16x64_i8 v[114:117], v[182:185], v[190:193], v[114:117]
	v_mfma_i32_16x16x64_i8 v[102:105], v[174:177], v[198:201], v[102:105]
	v_mfma_i32_16x16x64_i8 v[98:101], v[182:185], v[198:201], v[98:101]
	v_mfma_i32_16x16x64_i8 v[86:89], v[174:177], v[206:209], v[86:89]
	v_mfma_i32_16x16x64_i8 v[82:85], v[182:185], v[206:209], v[82:85]
	v_mfma_i32_16x16x64_i8 v[70:73], v[174:177], v[214:217], v[70:73]
	v_mfma_i32_16x16x64_i8 v[66:69], v[182:185], v[214:217], v[66:69]
	s_setprio 0
	s_barrier
	s_add_i32 s28, s73, s46
	v_lshl_add_u64 v[162:163], v[162:163], 0, s[14:15]
	s_mov_b32 m0, s28
	ds_read_b128 v[186:189], v169 offset:49152
	ds_read_b128 v[190:193], v169 offset:50176
	ds_read_b128 v[194:197], v169 offset:51200
	ds_read_b128 v[198:201], v169 offset:52224
	ds_read_b128 v[202:205], v169 offset:53248
	ds_read_b128 v[206:209], v169 offset:54272
	ds_read_b128 v[210:213], v169 offset:55296
	ds_read_b128 v[214:217], v169 offset:56320
	global_load_lds_dwordx4 v[162:163], off
	s_add_i32 m0, s28, 0x2000
	s_add_u32 s28, s34, 0x158080
	v_lshl_add_u64 v[162:163], v[218:219], 0, s[14:15]
	s_addc_u32 s29, s35, 0
	s_add_i32 s34, s74, s46
	global_load_lds_dwordx4 v[162:163], off
	v_lshl_add_u64 v[162:163], s[28:29], 0, v[150:151]
	s_mov_b32 m0, s34
	s_nop 0
	global_load_lds_dwordx4 v[162:163], off
	v_lshl_add_u64 v[162:163], s[28:29], 0, v[146:147]
	s_add_i32 m0, s34, 0x2000
	s_nop 0
	global_load_lds_dwordx4 v[162:163], off
	v_lshl_add_u64 v[162:163], v[220:221], 0, s[14:15]
	s_mov_b32 m0, s54
	s_nop 0
	global_load_lds_dwordx4 v[162:163], off
	v_lshl_add_u64 v[162:163], v[222:223], 0, s[14:15]
	s_mov_b32 m0, s55
	s_nop 0
	global_load_lds_dwordx4 v[162:163], off
	s_waitcnt vmcnt(8)
	s_waitcnt lgkmcnt(0)
	s_barrier
	s_setprio 1
	s_waitcnt lgkmcnt(0)
	v_mfma_i32_16x16x64_i8 v[62:65], v[130:133], v[186:189], v[62:65]
	v_mfma_i32_16x16x64_i8 v[58:61], v[138:141], v[186:189], v[58:61]
	v_mfma_i32_16x16x64_i8 v[46:49], v[130:133], v[194:197], v[46:49]
	v_mfma_i32_16x16x64_i8 v[42:45], v[138:141], v[194:197], v[42:45]
	v_mfma_i32_16x16x64_i8 v[30:33], v[130:133], v[202:205], v[30:33]
	v_mfma_i32_16x16x64_i8 v[26:29], v[138:141], v[202:205], v[26:29]
	v_mfma_i32_16x16x64_i8 v[14:17], v[130:133], v[210:213], v[14:17]
	v_mfma_i32_16x16x64_i8 v[10:13], v[138:141], v[210:213], v[10:13]
	v_mfma_i32_16x16x64_i8 v[62:65], v[134:137], v[190:193], v[62:65]
	v_mfma_i32_16x16x64_i8 v[58:61], v[142:145], v[190:193], v[58:61]
	v_mfma_i32_16x16x64_i8 v[46:49], v[134:137], v[198:201], v[46:49]
	v_mfma_i32_16x16x64_i8 v[42:45], v[142:145], v[198:201], v[42:45]
	v_mfma_i32_16x16x64_i8 v[30:33], v[134:137], v[206:209], v[30:33]
	v_mfma_i32_16x16x64_i8 v[26:29], v[142:145], v[206:209], v[26:29]
	v_mfma_i32_16x16x64_i8 v[14:17], v[134:137], v[214:217], v[14:17]
	v_mfma_i32_16x16x64_i8 v[10:13], v[142:145], v[214:217], v[10:13]
	s_setprio 0
	s_setprio 1
	v_mfma_i32_16x16x64_i8 v[54:57], v[170:173], v[186:189], v[54:57]
	v_mfma_i32_16x16x64_i8 v[50:53], v[178:181], v[186:189], v[50:53]
	v_mfma_i32_16x16x64_i8 v[38:41], v[170:173], v[194:197], v[38:41]
	v_mfma_i32_16x16x64_i8 v[34:37], v[178:181], v[194:197], v[34:37]
	v_mfma_i32_16x16x64_i8 v[22:25], v[170:173], v[202:205], v[22:25]
	v_mfma_i32_16x16x64_i8 v[18:21], v[178:181], v[202:205], v[18:21]
	v_mfma_i32_16x16x64_i8 v[6:9], v[170:173], v[210:213], v[6:9]
	v_mfma_i32_16x16x64_i8 v[2:5], v[178:181], v[210:213], v[2:5]
	v_mfma_i32_16x16x64_i8 v[54:57], v[174:177], v[190:193], v[54:57]
	v_mfma_i32_16x16x64_i8 v[50:53], v[182:185], v[190:193], v[50:53]
	v_mfma_i32_16x16x64_i8 v[38:41], v[174:177], v[198:201], v[38:41]
	v_mfma_i32_16x16x64_i8 v[34:37], v[182:185], v[198:201], v[34:37]
	v_mfma_i32_16x16x64_i8 v[22:25], v[174:177], v[206:209], v[22:25]
	v_mfma_i32_16x16x64_i8 v[18:21], v[182:185], v[206:209], v[18:21]
	v_mfma_i32_16x16x64_i8 v[6:9], v[174:177], v[214:217], v[6:9]
	v_mfma_i32_16x16x64_i8 v[2:5], v[182:185], v[214:217], v[2:5]
	s_setprio 0
	s_barrier
	s_add_i32 s72, s72, 2
	s_add_u32 s70, s70, 0x100
	s_addc_u32 s71, s71, 0
	s_cmpk_gt_u32 s72, 0x53
	s_mov_b64 s[28:29], s[30:31]
	s_cbranch_scc0 .LBB0_1099
	s_and_b64 vcc, exec, s[16:17]
	s_cbranch_vccz .LBB0_1102
	s_barrier

.LBB0_1246:
	ds_read_b128 v[130:133], v193
	ds_read_b128 v[134:137], v193 offset:1024
	ds_read_b128 v[138:141], v193 offset:2048
	ds_read_b128 v[142:145], v193 offset:3072
	ds_read_b128 v[162:165], v194
	ds_read_b128 v[166:169], v194 offset:1024
	ds_read_b128 v[170:173], v194 offset:2048
	ds_read_b128 v[174:177], v194 offset:3072
	s_add_u32 s30, s28, 0xfff00080
	s_addc_u32 s31, s29, -1
	s_cmp_eq_u32 s68, 60
	s_cselect_b32 s35, s3, s31
	s_cselect_b32 s34, s23, s30
	s_cselect_b32 s31, s17, s65
	s_cselect_b32 s30, s62, s63
	v_lshl_add_u64 v[216:217], s[28:29], 0, v[154:155]
	s_add_i32 m0, s45, 0xc000
	ds_read_b128 v[178:181], v195
	ds_read_b128 v[182:185], v195 offset:1024
	ds_read_b128 v[186:189], v195 offset:2048
	ds_read_b128 v[196:199], v195 offset:3072
	ds_read_b128 v[200:203], v195 offset:4096
	ds_read_b128 v[204:207], v195 offset:5120
	ds_read_b128 v[208:211], v195 offset:6144
	ds_read_b128 v[212:215], v195 offset:7168
	global_load_lds_dwordx4 v[216:217], off
	v_lshl_add_u64 v[216:217], s[28:29], 0, v[156:157]
	s_add_i32 m0, s45, 0xe000
	s_nop 0
	global_load_lds_dwordx4 v[216:217], off
	s_waitcnt vmcnt(8)
	s_waitcnt lgkmcnt(0)
	s_barrier
	s_nop 0
	s_setprio 1
	s_waitcnt lgkmcnt(0)
	v_mfma_f32_16x16x32_bf16 v[126:129], v[130:133], v[178:181], v[126:129]
	v_mfma_f32_16x16x32_bf16 v[122:125], v[138:141], v[178:181], v[122:125]
	v_mfma_f32_16x16x32_bf16 v[118:121], v[130:133], v[186:189], v[118:121]
	v_mfma_f32_16x16x32_bf16 v[110:113], v[138:141], v[186:189], v[110:113]
	v_mfma_f32_16x16x32_bf16 v[98:101], v[130:133], v[200:203], v[98:101]
	v_mfma_f32_16x16x32_bf16 v[90:93], v[138:141], v[200:203], v[90:93]
	v_mfma_f32_16x16x32_bf16 v[82:85], v[130:133], v[208:211], v[82:85]
	v_mfma_f32_16x16x32_bf16 v[74:77], v[138:141], v[208:211], v[74:77]
	v_mfma_f32_16x16x32_bf16 v[126:129], v[134:137], v[182:185], v[126:129]
	v_mfma_f32_16x16x32_bf16 v[122:125], v[142:145], v[182:185], v[122:125]
	v_mfma_f32_16x16x32_bf16 v[118:121], v[134:137], v[196:199], v[118:121]
	v_mfma_f32_16x16x32_bf16 v[110:113], v[142:145], v[196:199], v[110:113]
	v_mfma_f32_16x16x32_bf16 v[98:101], v[134:137], v[204:207], v[98:101]
	v_mfma_f32_16x16x32_bf16 v[90:93], v[142:145], v[204:207], v[90:93]
	v_mfma_f32_16x16x32_bf16 v[82:85], v[134:137], v[212:215], v[82:85]
	v_mfma_f32_16x16x32_bf16 v[74:77], v[142:145], v[212:215], v[74:77]
	s_setprio 0
	s_setprio 1
	v_mfma_f32_16x16x32_bf16 v[114:117], v[162:165], v[178:181], v[114:117]
	v_mfma_f32_16x16x32_bf16 v[106:109], v[170:173], v[178:181], v[106:109]
	v_mfma_f32_16x16x32_bf16 v[102:105], v[162:165], v[186:189], v[102:105]
	v_mfma_f32_16x16x32_bf16 v[94:97], v[170:173], v[186:189], v[94:97]
	v_mfma_f32_16x16x32_bf16 v[86:89], v[162:165], v[200:203], v[86:89]
	v_mfma_f32_16x16x32_bf16 v[78:81], v[170:173], v[200:203], v[78:81]
	v_mfma_f32_16x16x32_bf16 v[70:73], v[162:165], v[208:211], v[70:73]
	v_mfma_f32_16x16x32_bf16 v[66:69], v[170:173], v[208:211], v[66:69]
	v_mfma_f32_16x16x32_bf16 v[114:117], v[166:169], v[182:185], v[114:117]
	v_mfma_f32_16x16x32_bf16 v[106:109], v[174:177], v[182:185], v[106:109]
	v_mfma_f32_16x16x32_bf16 v[102:105], v[166:169], v[196:199], v[102:105]
	v_mfma_f32_16x16x32_bf16 v[94:97], v[174:177], v[196:199], v[94:97]
	v_mfma_f32_16x16x32_bf16 v[86:89], v[166:169], v[204:207], v[86:89]
	v_mfma_f32_16x16x32_bf16 v[78:81], v[174:177], v[204:207], v[78:81]
	v_mfma_f32_16x16x32_bf16 v[70:73], v[166:169], v[212:215], v[70:73]
	v_mfma_f32_16x16x32_bf16 v[66:69], v[174:177], v[212:215], v[66:69]
	s_setprio 0
	s_barrier
	s_add_i32 s69, s58, s44
	v_lshl_add_u64 v[216:217], s[30:31], 0, v[148:149]
	s_mov_b32 m0, s69
	ds_read_b128 v[178:181], v195 offset:16384
	ds_read_b128 v[182:185], v195 offset:17408
	ds_read_b128 v[186:189], v195 offset:18432
	ds_read_b128 v[196:199], v195 offset:19456
	ds_read_b128 v[200:203], v195 offset:20480
	ds_read_b128 v[204:207], v195 offset:21504
	ds_read_b128 v[208:211], v195 offset:22528
	ds_read_b128 v[212:215], v195 offset:23552
	global_load_lds_dwordx4 v[216:217], off
	s_add_i32 m0, s69, 0x2000
	s_add_u32 s70, s30, 0x100000
	v_lshl_add_u64 v[218:219], s[30:31], 0, v[152:153]
	s_addc_u32 s71, s31, 0
	s_add_i32 s69, s59, s44
	global_load_lds_dwordx4 v[218:219], off
	v_lshl_add_u64 v[220:221], s[70:71], 0, v[148:149]
	s_mov_b32 m0, s69
	v_lshl_add_u64 v[222:223], s[34:35], 0, v[150:151]
	global_load_lds_dwordx4 v[220:221], off
	v_lshl_add_u64 v[220:221], s[70:71], 0, v[152:153]
	s_add_i32 m0, s69, 0x2000
	s_nop 0
	global_load_lds_dwordx4 v[220:221], off
	v_lshl_add_u64 v[220:221], s[34:35], 0, v[146:147]
	s_mov_b32 m0, s45
	s_nop 0
	global_load_lds_dwordx4 v[220:221], off
	s_mov_b32 m0, s46
	s_nop 0
	global_load_lds_dwordx4 v[222:223], off
	s_waitcnt vmcnt(8)
	s_waitcnt lgkmcnt(0)
	s_barrier
	s_nop 0
	s_setprio 1
	s_waitcnt lgkmcnt(0)
	v_mfma_f32_16x16x32_bf16 v[62:65], v[130:133], v[178:181], v[62:65]
	v_mfma_f32_16x16x32_bf16 v[58:61], v[138:141], v[178:181], v[58:61]
	v_mfma_f32_16x16x32_bf16 v[46:49], v[130:133], v[186:189], v[46:49]
	v_mfma_f32_16x16x32_bf16 v[42:45], v[138:141], v[186:189], v[42:45]
	v_mfma_f32_16x16x32_bf16 v[30:33], v[130:133], v[200:203], v[30:33]
	v_mfma_f32_16x16x32_bf16 v[26:29], v[138:141], v[200:203], v[26:29]
	v_mfma_f32_16x16x32_bf16 v[14:17], v[130:133], v[208:211], v[14:17]
	v_mfma_f32_16x16x32_bf16 v[10:13], v[138:141], v[208:211], v[10:13]
	v_mfma_f32_16x16x32_bf16 v[62:65], v[134:137], v[182:185], v[62:65]
	v_mfma_f32_16x16x32_bf16 v[58:61], v[142:145], v[182:185], v[58:61]
	v_mfma_f32_16x16x32_bf16 v[46:49], v[134:137], v[196:199], v[46:49]
	v_mfma_f32_16x16x32_bf16 v[42:45], v[142:145], v[196:199], v[42:45]
	v_mfma_f32_16x16x32_bf16 v[30:33], v[134:137], v[204:207], v[30:33]
	v_mfma_f32_16x16x32_bf16 v[26:29], v[142:145], v[204:207], v[26:29]
	v_mfma_f32_16x16x32_bf16 v[14:17], v[134:137], v[212:215], v[14:17]
	v_mfma_f32_16x16x32_bf16 v[10:13], v[142:145], v[212:215], v[10:13]
	s_setprio 0
	s_setprio 1
	v_mfma_f32_16x16x32_bf16 v[54:57], v[162:165], v[178:181], v[54:57]
	v_mfma_f32_16x16x32_bf16 v[50:53], v[170:173], v[178:181], v[50:53]
	v_mfma_f32_16x16x32_bf16 v[38:41], v[162:165], v[186:189], v[38:41]
	v_mfma_f32_16x16x32_bf16 v[34:37], v[170:173], v[186:189], v[34:37]
	v_mfma_f32_16x16x32_bf16 v[22:25], v[162:165], v[200:203], v[22:25]
	v_mfma_f32_16x16x32_bf16 v[18:21], v[170:173], v[200:203], v[18:21]
	v_mfma_f32_16x16x32_bf16 v[6:9], v[162:165], v[208:211], v[6:9]
	v_mfma_f32_16x16x32_bf16 v[2:5], v[170:173], v[208:211], v[2:5]
	v_mfma_f32_16x16x32_bf16 v[54:57], v[166:169], v[182:185], v[54:57]
	v_mfma_f32_16x16x32_bf16 v[50:53], v[174:177], v[182:185], v[50:53]
	v_mfma_f32_16x16x32_bf16 v[38:41], v[166:169], v[196:199], v[38:41]
	v_mfma_f32_16x16x32_bf16 v[34:37], v[174:177], v[196:199], v[34:37]
	v_mfma_f32_16x16x32_bf16 v[22:25], v[166:169], v[204:207], v[22:25]
	v_mfma_f32_16x16x32_bf16 v[18:21], v[174:177], v[204:207], v[18:21]
	v_mfma_f32_16x16x32_bf16 v[6:9], v[166:169], v[212:215], v[6:9]
	v_mfma_f32_16x16x32_bf16 v[2:5], v[174:177], v[212:215], v[2:5]
	s_setprio 0
	s_barrier
	s_add_i32 s69, 0, 0x18000
	s_add_i32 s70, 0, 0x1c000
	v_add_u32_e32 v142, s69, v192
	v_add_u32_e32 v174, s70, v192
	ds_read_b128 v[130:133], v142
	ds_read_b128 v[134:137], v142 offset:1024
	ds_read_b128 v[138:141], v142 offset:2048
	ds_read_b128 v[142:145], v142 offset:3072
	ds_read_b128 v[162:165], v174
	ds_read_b128 v[166:169], v174 offset:1024
	ds_read_b128 v[170:173], v174 offset:2048
	ds_read_b128 v[174:177], v174 offset:3072
	s_add_u32 s34, s34, 0x100000
	s_addc_u32 s35, s35, 0
	s_mov_b32 m0, s47
	v_lshl_add_u64 v[224:225], s[34:35], 0, v[146:147]
	ds_read_b128 v[178:181], v195 offset:32768
	ds_read_b128 v[182:185], v195 offset:33792
	ds_read_b128 v[186:189], v195 offset:34816
	ds_read_b128 v[196:199], v195 offset:35840
	ds_read_b128 v[200:203], v195 offset:36864
	ds_read_b128 v[204:207], v195 offset:37888
	ds_read_b128 v[208:211], v195 offset:38912
	ds_read_b128 v[212:215], v195 offset:39936
	global_load_lds_dwordx4 v[224:225], off
	v_lshl_add_u64 v[224:225], s[34:35], 0, v[150:151]
	s_mov_b32 m0, s48
	s_nop 0
	global_load_lds_dwordx4 v[224:225], off
	s_waitcnt vmcnt(8)
	s_waitcnt lgkmcnt(0)
	s_barrier
	s_nop 0
	s_setprio 1
	s_waitcnt lgkmcnt(0)
	v_mfma_f32_16x16x32_bf16 v[126:129], v[130:133], v[178:181], v[126:129]
	v_mfma_f32_16x16x32_bf16 v[122:125], v[138:141], v[178:181], v[122:125]
	v_mfma_f32_16x16x32_bf16 v[118:121], v[130:133], v[186:189], v[118:121]
	v_mfma_f32_16x16x32_bf16 v[110:113], v[138:141], v[186:189], v[110:113]
	v_mfma_f32_16x16x32_bf16 v[98:101], v[130:133], v[200:203], v[98:101]
	v_mfma_f32_16x16x32_bf16 v[90:93], v[138:141], v[200:203], v[90:93]
	v_mfma_f32_16x16x32_bf16 v[82:85], v[130:133], v[208:211], v[82:85]
	v_mfma_f32_16x16x32_bf16 v[74:77], v[138:141], v[208:211], v[74:77]
	v_mfma_f32_16x16x32_bf16 v[126:129], v[134:137], v[182:185], v[126:129]
	v_mfma_f32_16x16x32_bf16 v[122:125], v[142:145], v[182:185], v[122:125]
	v_mfma_f32_16x16x32_bf16 v[118:121], v[134:137], v[196:199], v[118:121]
	v_mfma_f32_16x16x32_bf16 v[110:113], v[142:145], v[196:199], v[110:113]
	v_mfma_f32_16x16x32_bf16 v[98:101], v[134:137], v[204:207], v[98:101]
	v_mfma_f32_16x16x32_bf16 v[90:93], v[142:145], v[204:207], v[90:93]
	v_mfma_f32_16x16x32_bf16 v[82:85], v[134:137], v[212:215], v[82:85]
	v_mfma_f32_16x16x32_bf16 v[74:77], v[142:145], v[212:215], v[74:77]
	s_setprio 0
	s_setprio 1
	v_mfma_f32_16x16x32_bf16 v[114:117], v[162:165], v[178:181], v[114:117]
	v_mfma_f32_16x16x32_bf16 v[106:109], v[170:173], v[178:181], v[106:109]
	v_mfma_f32_16x16x32_bf16 v[102:105], v[162:165], v[186:189], v[102:105]
	v_mfma_f32_16x16x32_bf16 v[94:97], v[170:173], v[186:189], v[94:97]
	v_mfma_f32_16x16x32_bf16 v[86:89], v[162:165], v[200:203], v[86:89]
	v_mfma_f32_16x16x32_bf16 v[78:81], v[170:173], v[200:203], v[78:81]
	v_mfma_f32_16x16x32_bf16 v[70:73], v[162:165], v[208:211], v[70:73]
	v_mfma_f32_16x16x32_bf16 v[66:69], v[170:173], v[208:211], v[66:69]
	v_mfma_f32_16x16x32_bf16 v[114:117], v[166:169], v[182:185], v[114:117]
	v_mfma_f32_16x16x32_bf16 v[106:109], v[174:177], v[182:185], v[106:109]
	v_mfma_f32_16x16x32_bf16 v[102:105], v[166:169], v[196:199], v[102:105]
	v_mfma_f32_16x16x32_bf16 v[94:97], v[174:177], v[196:199], v[94:97]
	v_mfma_f32_16x16x32_bf16 v[86:89], v[166:169], v[204:207], v[86:89]
	v_mfma_f32_16x16x32_bf16 v[78:81], v[174:177], v[204:207], v[78:81]
	v_mfma_f32_16x16x32_bf16 v[70:73], v[166:169], v[212:215], v[70:73]
	v_mfma_f32_16x16x32_bf16 v[66:69], v[174:177], v[212:215], v[66:69]
	s_setprio 0
	s_barrier
	s_add_i32 s34, s69, s44
	v_lshl_add_u64 v[216:217], v[216:217], 0, s[12:13]
	s_mov_b32 m0, s34
	ds_read_b128 v[178:181], v195 offset:49152
	ds_read_b128 v[182:185], v195 offset:50176
	ds_read_b128 v[186:189], v195 offset:51200
	ds_read_b128 v[196:199], v195 offset:52224
	ds_read_b128 v[200:203], v195 offset:53248
	ds_read_b128 v[204:207], v195 offset:54272
	ds_read_b128 v[208:211], v195 offset:55296
	ds_read_b128 v[212:215], v195 offset:56320
	global_load_lds_dwordx4 v[216:217], off
	s_add_i32 m0, s34, 0x2000
	s_add_u32 s30, s30, 0x100080
	v_lshl_add_u64 v[216:217], v[218:219], 0, s[12:13]
	s_addc_u32 s31, s31, 0
	s_add_i32 s34, s70, s44
	global_load_lds_dwordx4 v[216:217], off
	v_lshl_add_u64 v[216:217], s[30:31], 0, v[148:149]
	s_mov_b32 m0, s34
	s_nop 0
	global_load_lds_dwordx4 v[216:217], off
	v_lshl_add_u64 v[216:217], s[30:31], 0, v[152:153]
	s_add_i32 m0, s34, 0x2000
	s_nop 0
	global_load_lds_dwordx4 v[216:217], off
	v_lshl_add_u64 v[216:217], v[220:221], 0, s[12:13]
	s_mov_b32 m0, s55
	s_nop 0
	global_load_lds_dwordx4 v[216:217], off
	v_lshl_add_u64 v[216:217], v[222:223], 0, s[12:13]
	s_mov_b32 m0, s56
	s_nop 0
	global_load_lds_dwordx4 v[216:217], off
	s_waitcnt vmcnt(8)
	s_waitcnt lgkmcnt(0)
	s_barrier
	s_setprio 1
	s_waitcnt lgkmcnt(0)
	v_mfma_f32_16x16x32_bf16 v[62:65], v[130:133], v[178:181], v[62:65]
	v_mfma_f32_16x16x32_bf16 v[58:61], v[138:141], v[178:181], v[58:61]
	v_mfma_f32_16x16x32_bf16 v[46:49], v[130:133], v[186:189], v[46:49]
	v_mfma_f32_16x16x32_bf16 v[42:45], v[138:141], v[186:189], v[42:45]
	v_mfma_f32_16x16x32_bf16 v[30:33], v[130:133], v[200:203], v[30:33]
	v_mfma_f32_16x16x32_bf16 v[26:29], v[138:141], v[200:203], v[26:29]
	v_mfma_f32_16x16x32_bf16 v[14:17], v[130:133], v[208:211], v[14:17]
	v_mfma_f32_16x16x32_bf16 v[10:13], v[138:141], v[208:211], v[10:13]
	v_mfma_f32_16x16x32_bf16 v[62:65], v[134:137], v[182:185], v[62:65]
	v_mfma_f32_16x16x32_bf16 v[58:61], v[142:145], v[182:185], v[58:61]
	v_mfma_f32_16x16x32_bf16 v[46:49], v[134:137], v[196:199], v[46:49]
	v_mfma_f32_16x16x32_bf16 v[42:45], v[142:145], v[196:199], v[42:45]
	v_mfma_f32_16x16x32_bf16 v[30:33], v[134:137], v[204:207], v[30:33]
	v_mfma_f32_16x16x32_bf16 v[26:29], v[142:145], v[204:207], v[26:29]
	v_mfma_f32_16x16x32_bf16 v[14:17], v[134:137], v[212:215], v[14:17]
	v_mfma_f32_16x16x32_bf16 v[10:13], v[142:145], v[212:215], v[10:13]
	s_setprio 0
	s_setprio 1
	v_mfma_f32_16x16x32_bf16 v[54:57], v[162:165], v[178:181], v[54:57]
	v_mfma_f32_16x16x32_bf16 v[50:53], v[170:173], v[178:181], v[50:53]
	v_mfma_f32_16x16x32_bf16 v[38:41], v[162:165], v[186:189], v[38:41]
	v_mfma_f32_16x16x32_bf16 v[34:37], v[170:173], v[186:189], v[34:37]
	v_mfma_f32_16x16x32_bf16 v[22:25], v[162:165], v[200:203], v[22:25]
	v_mfma_f32_16x16x32_bf16 v[18:21], v[170:173], v[200:203], v[18:21]
	v_mfma_f32_16x16x32_bf16 v[6:9], v[162:165], v[208:211], v[6:9]
	v_mfma_f32_16x16x32_bf16 v[2:5], v[170:173], v[208:211], v[2:5]
	v_mfma_f32_16x16x32_bf16 v[54:57], v[166:169], v[182:185], v[54:57]
	v_mfma_f32_16x16x32_bf16 v[50:53], v[174:177], v[182:185], v[50:53]
	v_mfma_f32_16x16x32_bf16 v[38:41], v[166:169], v[196:199], v[38:41]
	v_mfma_f32_16x16x32_bf16 v[34:37], v[174:177], v[196:199], v[34:37]
	v_mfma_f32_16x16x32_bf16 v[22:25], v[166:169], v[204:207], v[22:25]
	v_mfma_f32_16x16x32_bf16 v[18:21], v[174:177], v[204:207], v[18:21]
	v_mfma_f32_16x16x32_bf16 v[6:9], v[166:169], v[212:215], v[6:9]
	v_mfma_f32_16x16x32_bf16 v[2:5], v[174:177], v[212:215], v[2:5]
	s_setprio 0
	s_barrier
	s_add_i32 s68, s68, 2
	s_add_u32 s28, s28, 0x100
	s_addc_u32 s29, s29, 0
	s_add_u32 s63, s63, 0x100
	s_addc_u32 s65, s65, 0
	s_cmp_gt_u32 s68, 61
	s_cbranch_scc0 .LBB0_1246
	s_and_b64 vcc, exec, s[14:15]
	s_cbranch_vccz .LBB0_1249
	s_barrier

.LBB0_1521:
	ds_read_b128 v[130:133], v169
	ds_read_b128 v[134:137], v169 offset:1024
	ds_read_b128 v[138:141], v169 offset:2048
	ds_read_b128 v[142:145], v169 offset:3072
	ds_read_b128 v[162:165], v170
	ds_read_b128 v[172:175], v170 offset:1024
	ds_read_b128 v[176:179], v170 offset:2048
	ds_read_b128 v[180:183], v170 offset:3072
	s_add_u32 s38, s2, 0xfff00080
	s_addc_u32 s39, s3, -1
	s_cmp_eq_u32 s69, 60
	s_cselect_b32 s45, s29, s39
	s_cselect_b32 s44, s65, s38
	s_cselect_b32 s39, s27, s68
	s_cselect_b32 s38, s66, s67
	v_lshl_add_u64 v[216:217], s[2:3], 0, v[154:155]
	s_add_i32 m0, s37, 0xc000
	ds_read_b128 v[184:187], v171
	ds_read_b128 v[188:191], v171 offset:1024
	ds_read_b128 v[192:195], v171 offset:2048
	ds_read_b128 v[196:199], v171 offset:3072
	ds_read_b128 v[200:203], v171 offset:4096
	ds_read_b128 v[204:207], v171 offset:5120
	ds_read_b128 v[208:211], v171 offset:6144
	ds_read_b128 v[212:215], v171 offset:7168
	global_load_lds_dwordx4 v[216:217], off
	v_lshl_add_u64 v[216:217], s[2:3], 0, v[156:157]
	s_add_i32 m0, s37, 0xe000
	s_nop 0
	global_load_lds_dwordx4 v[216:217], off
	s_waitcnt vmcnt(8)
	s_waitcnt lgkmcnt(0)
	s_barrier
	s_setprio 1
	s_waitcnt lgkmcnt(0)
	v_mfma_f32_16x16x32_bf16 v[126:129], v[130:133], v[184:187], v[126:129]
	v_mfma_f32_16x16x32_bf16 v[122:125], v[138:141], v[184:187], v[122:125]
	v_mfma_f32_16x16x32_bf16 v[114:117], v[130:133], v[192:195], v[114:117]
	v_mfma_f32_16x16x32_bf16 v[106:109], v[138:141], v[192:195], v[106:109]
	v_mfma_f32_16x16x32_bf16 v[98:101], v[130:133], v[200:203], v[98:101]
	v_mfma_f32_16x16x32_bf16 v[90:93], v[138:141], v[200:203], v[90:93]
	v_mfma_f32_16x16x32_bf16 v[82:85], v[130:133], v[208:211], v[82:85]
	v_mfma_f32_16x16x32_bf16 v[74:77], v[138:141], v[208:211], v[74:77]
	v_mfma_f32_16x16x32_bf16 v[126:129], v[134:137], v[188:191], v[126:129]
	v_mfma_f32_16x16x32_bf16 v[122:125], v[142:145], v[188:191], v[122:125]
	v_mfma_f32_16x16x32_bf16 v[114:117], v[134:137], v[196:199], v[114:117]
	v_mfma_f32_16x16x32_bf16 v[106:109], v[142:145], v[196:199], v[106:109]
	v_mfma_f32_16x16x32_bf16 v[98:101], v[134:137], v[204:207], v[98:101]
	v_mfma_f32_16x16x32_bf16 v[90:93], v[142:145], v[204:207], v[90:93]
	v_mfma_f32_16x16x32_bf16 v[82:85], v[134:137], v[212:215], v[82:85]
	v_mfma_f32_16x16x32_bf16 v[74:77], v[142:145], v[212:215], v[74:77]
	s_setprio 0
	s_setprio 1
	v_mfma_f32_16x16x32_bf16 v[118:121], v[162:165], v[184:187], v[118:121]
	v_mfma_f32_16x16x32_bf16 v[110:113], v[176:179], v[184:187], v[110:113]
	v_mfma_f32_16x16x32_bf16 v[102:105], v[162:165], v[192:195], v[102:105]
	v_mfma_f32_16x16x32_bf16 v[94:97], v[176:179], v[192:195], v[94:97]
	v_mfma_f32_16x16x32_bf16 v[86:89], v[162:165], v[200:203], v[86:89]
	v_mfma_f32_16x16x32_bf16 v[78:81], v[176:179], v[200:203], v[78:81]
	v_mfma_f32_16x16x32_bf16 v[70:73], v[162:165], v[208:211], v[70:73]
	v_mfma_f32_16x16x32_bf16 v[66:69], v[176:179], v[208:211], v[66:69]
	v_mfma_f32_16x16x32_bf16 v[118:121], v[172:175], v[188:191], v[118:121]
	v_mfma_f32_16x16x32_bf16 v[110:113], v[180:183], v[188:191], v[110:113]
	v_mfma_f32_16x16x32_bf16 v[102:105], v[172:175], v[196:199], v[102:105]
	v_mfma_f32_16x16x32_bf16 v[94:97], v[180:183], v[196:199], v[94:97]
	v_mfma_f32_16x16x32_bf16 v[86:89], v[172:175], v[204:207], v[86:89]
	v_mfma_f32_16x16x32_bf16 v[78:81], v[180:183], v[204:207], v[78:81]
	v_mfma_f32_16x16x32_bf16 v[70:73], v[172:175], v[212:215], v[70:73]
	v_mfma_f32_16x16x32_bf16 v[66:69], v[180:183], v[212:215], v[66:69]
	s_setprio 0
	s_barrier
	s_add_i32 s43, s57, s50
	v_lshl_add_u64 v[216:217], s[38:39], 0, v[150:151]
	s_mov_b32 m0, s43
	ds_read_b128 v[184:187], v171 offset:16384
	ds_read_b128 v[188:191], v171 offset:17408
	ds_read_b128 v[192:195], v171 offset:18432
	ds_read_b128 v[196:199], v171 offset:19456
	ds_read_b128 v[200:203], v171 offset:20480
	ds_read_b128 v[204:207], v171 offset:21504
	ds_read_b128 v[208:211], v171 offset:22528
	ds_read_b128 v[212:215], v171 offset:23552
	global_load_lds_dwordx4 v[216:217], off
	s_add_i32 m0, s43, 0x2000
	s_add_u32 s70, s38, 0x100000
	v_lshl_add_u64 v[218:219], s[38:39], 0, v[146:147]
	s_addc_u32 s71, s39, 0
	s_add_i32 s43, s58, s50
	global_load_lds_dwordx4 v[218:219], off
	v_lshl_add_u64 v[220:221], s[70:71], 0, v[150:151]
	s_mov_b32 m0, s43
	v_lshl_add_u64 v[222:223], s[44:45], 0, v[148:149]
	global_load_lds_dwordx4 v[220:221], off
	v_lshl_add_u64 v[220:221], s[70:71], 0, v[146:147]
	s_add_i32 m0, s43, 0x2000
	s_nop 0
	global_load_lds_dwordx4 v[220:221], off
	v_lshl_add_u64 v[220:221], s[44:45], 0, v[152:153]
	s_mov_b32 m0, s37
	s_nop 0
	global_load_lds_dwordx4 v[220:221], off
	s_mov_b32 m0, s51
	s_nop 0
	global_load_lds_dwordx4 v[222:223], off
	s_waitcnt vmcnt(8)
	s_waitcnt lgkmcnt(0)
	s_barrier
	s_nop 0
	s_setprio 1
	s_waitcnt lgkmcnt(0)
	v_mfma_f32_16x16x32_bf16 v[62:65], v[130:133], v[184:187], v[62:65]
	v_mfma_f32_16x16x32_bf16 v[58:61], v[138:141], v[184:187], v[58:61]
	v_mfma_f32_16x16x32_bf16 v[50:53], v[130:133], v[192:195], v[50:53]
	v_mfma_f32_16x16x32_bf16 v[42:45], v[138:141], v[192:195], v[42:45]
	v_mfma_f32_16x16x32_bf16 v[34:37], v[130:133], v[200:203], v[34:37]
	v_mfma_f32_16x16x32_bf16 v[26:29], v[138:141], v[200:203], v[26:29]
	v_mfma_f32_16x16x32_bf16 v[18:21], v[130:133], v[208:211], v[18:21]
	v_mfma_f32_16x16x32_bf16 v[10:13], v[138:141], v[208:211], v[10:13]
	v_mfma_f32_16x16x32_bf16 v[62:65], v[134:137], v[188:191], v[62:65]
	v_mfma_f32_16x16x32_bf16 v[58:61], v[142:145], v[188:191], v[58:61]
	v_mfma_f32_16x16x32_bf16 v[50:53], v[134:137], v[196:199], v[50:53]
	v_mfma_f32_16x16x32_bf16 v[42:45], v[142:145], v[196:199], v[42:45]
	v_mfma_f32_16x16x32_bf16 v[34:37], v[134:137], v[204:207], v[34:37]
	v_mfma_f32_16x16x32_bf16 v[26:29], v[142:145], v[204:207], v[26:29]
	v_mfma_f32_16x16x32_bf16 v[18:21], v[134:137], v[212:215], v[18:21]
	v_mfma_f32_16x16x32_bf16 v[10:13], v[142:145], v[212:215], v[10:13]
	s_setprio 0
	s_setprio 1
	v_mfma_f32_16x16x32_bf16 v[54:57], v[162:165], v[184:187], v[54:57]
	v_mfma_f32_16x16x32_bf16 v[46:49], v[176:179], v[184:187], v[46:49]
	v_mfma_f32_16x16x32_bf16 v[38:41], v[162:165], v[192:195], v[38:41]
	v_mfma_f32_16x16x32_bf16 v[30:33], v[176:179], v[192:195], v[30:33]
	v_mfma_f32_16x16x32_bf16 v[22:25], v[162:165], v[200:203], v[22:25]
	v_mfma_f32_16x16x32_bf16 v[14:17], v[176:179], v[200:203], v[14:17]
	v_mfma_f32_16x16x32_bf16 v[6:9], v[162:165], v[208:211], v[6:9]
	v_mfma_f32_16x16x32_bf16 v[2:5], v[176:179], v[208:211], v[2:5]
	v_mfma_f32_16x16x32_bf16 v[54:57], v[172:175], v[188:191], v[54:57]
	v_mfma_f32_16x16x32_bf16 v[46:49], v[180:183], v[188:191], v[46:49]
	v_mfma_f32_16x16x32_bf16 v[38:41], v[172:175], v[196:199], v[38:41]
	v_mfma_f32_16x16x32_bf16 v[30:33], v[180:183], v[196:199], v[30:33]
	v_mfma_f32_16x16x32_bf16 v[22:25], v[172:175], v[204:207], v[22:25]
	v_mfma_f32_16x16x32_bf16 v[14:17], v[180:183], v[204:207], v[14:17]
	v_mfma_f32_16x16x32_bf16 v[6:9], v[172:175], v[212:215], v[6:9]
	v_mfma_f32_16x16x32_bf16 v[2:5], v[180:183], v[212:215], v[2:5]
	s_setprio 0
	s_barrier
	s_add_i32 s43, 0, 0x18000
	s_add_i32 s70, 0, 0x1c000
	v_add_u32_e32 v142, s43, v167
	v_add_u32_e32 v180, s70, v167
	ds_read_b128 v[130:133], v142
	ds_read_b128 v[134:137], v142 offset:1024
	ds_read_b128 v[138:141], v142 offset:2048
	ds_read_b128 v[142:145], v142 offset:3072
	ds_read_b128 v[162:165], v180
	ds_read_b128 v[172:175], v180 offset:1024
	ds_read_b128 v[176:179], v180 offset:2048
	ds_read_b128 v[180:183], v180 offset:3072
	s_add_u32 s44, s44, 0x100000
	s_addc_u32 s45, s45, 0
	s_mov_b32 m0, s52
	v_lshl_add_u64 v[224:225], s[44:45], 0, v[152:153]
	ds_read_b128 v[184:187], v171 offset:32768
	ds_read_b128 v[188:191], v171 offset:33792
	ds_read_b128 v[192:195], v171 offset:34816
	ds_read_b128 v[196:199], v171 offset:35840
	ds_read_b128 v[200:203], v171 offset:36864
	ds_read_b128 v[204:207], v171 offset:37888
	ds_read_b128 v[208:211], v171 offset:38912
	ds_read_b128 v[212:215], v171 offset:39936
	global_load_lds_dwordx4 v[224:225], off
	v_lshl_add_u64 v[224:225], s[44:45], 0, v[148:149]
	s_mov_b32 m0, s53
	s_nop 0
	global_load_lds_dwordx4 v[224:225], off
	s_waitcnt vmcnt(8)
	s_waitcnt lgkmcnt(0)
	s_barrier
	s_nop 0
	s_setprio 1
	s_waitcnt lgkmcnt(0)
	v_mfma_f32_16x16x32_bf16 v[126:129], v[130:133], v[184:187], v[126:129]
	v_mfma_f32_16x16x32_bf16 v[122:125], v[138:141], v[184:187], v[122:125]
	v_mfma_f32_16x16x32_bf16 v[114:117], v[130:133], v[192:195], v[114:117]
	v_mfma_f32_16x16x32_bf16 v[106:109], v[138:141], v[192:195], v[106:109]
	v_mfma_f32_16x16x32_bf16 v[98:101], v[130:133], v[200:203], v[98:101]
	v_mfma_f32_16x16x32_bf16 v[90:93], v[138:141], v[200:203], v[90:93]
	v_mfma_f32_16x16x32_bf16 v[82:85], v[130:133], v[208:211], v[82:85]
	v_mfma_f32_16x16x32_bf16 v[74:77], v[138:141], v[208:211], v[74:77]
	v_mfma_f32_16x16x32_bf16 v[126:129], v[134:137], v[188:191], v[126:129]
	v_mfma_f32_16x16x32_bf16 v[122:125], v[142:145], v[188:191], v[122:125]
	v_mfma_f32_16x16x32_bf16 v[114:117], v[134:137], v[196:199], v[114:117]
	v_mfma_f32_16x16x32_bf16 v[106:109], v[142:145], v[196:199], v[106:109]
	v_mfma_f32_16x16x32_bf16 v[98:101], v[134:137], v[204:207], v[98:101]
	v_mfma_f32_16x16x32_bf16 v[90:93], v[142:145], v[204:207], v[90:93]
	v_mfma_f32_16x16x32_bf16 v[82:85], v[134:137], v[212:215], v[82:85]
	v_mfma_f32_16x16x32_bf16 v[74:77], v[142:145], v[212:215], v[74:77]
	s_setprio 0
	s_setprio 1
	v_mfma_f32_16x16x32_bf16 v[118:121], v[162:165], v[184:187], v[118:121]
	v_mfma_f32_16x16x32_bf16 v[110:113], v[176:179], v[184:187], v[110:113]
	v_mfma_f32_16x16x32_bf16 v[102:105], v[162:165], v[192:195], v[102:105]
	v_mfma_f32_16x16x32_bf16 v[94:97], v[176:179], v[192:195], v[94:97]
	v_mfma_f32_16x16x32_bf16 v[86:89], v[162:165], v[200:203], v[86:89]
	v_mfma_f32_16x16x32_bf16 v[78:81], v[176:179], v[200:203], v[78:81]
	v_mfma_f32_16x16x32_bf16 v[70:73], v[162:165], v[208:211], v[70:73]
	v_mfma_f32_16x16x32_bf16 v[66:69], v[176:179], v[208:211], v[66:69]
	v_mfma_f32_16x16x32_bf16 v[118:121], v[172:175], v[188:191], v[118:121]
	v_mfma_f32_16x16x32_bf16 v[110:113], v[180:183], v[188:191], v[110:113]
	v_mfma_f32_16x16x32_bf16 v[102:105], v[172:175], v[196:199], v[102:105]
	v_mfma_f32_16x16x32_bf16 v[94:97], v[180:183], v[196:199], v[94:97]
	v_mfma_f32_16x16x32_bf16 v[86:89], v[172:175], v[204:207], v[86:89]
	v_mfma_f32_16x16x32_bf16 v[78:81], v[180:183], v[204:207], v[78:81]
	v_mfma_f32_16x16x32_bf16 v[70:73], v[172:175], v[212:215], v[70:73]
	v_mfma_f32_16x16x32_bf16 v[66:69], v[180:183], v[212:215], v[66:69]
	s_setprio 0
	s_barrier
	s_add_i32 s43, s43, s50
	v_lshl_add_u64 v[216:217], v[216:217], 0, s[16:17]
	s_mov_b32 m0, s43
	ds_read_b128 v[184:187], v171 offset:49152
	ds_read_b128 v[188:191], v171 offset:50176
	ds_read_b128 v[192:195], v171 offset:51200
	ds_read_b128 v[196:199], v171 offset:52224
	ds_read_b128 v[200:203], v171 offset:53248
	ds_read_b128 v[204:207], v171 offset:54272
	ds_read_b128 v[208:211], v171 offset:55296
	ds_read_b128 v[212:215], v171 offset:56320
	global_load_lds_dwordx4 v[216:217], off
	s_add_i32 m0, s43, 0x2000
	s_add_u32 s38, s38, 0x100080
	v_lshl_add_u64 v[216:217], v[218:219], 0, s[16:17]
	s_addc_u32 s39, s39, 0
	s_add_i32 s43, s70, s50
	global_load_lds_dwordx4 v[216:217], off
	v_lshl_add_u64 v[216:217], s[38:39], 0, v[150:151]
	s_mov_b32 m0, s43
	s_nop 0
	global_load_lds_dwordx4 v[216:217], off
	v_lshl_add_u64 v[216:217], s[38:39], 0, v[146:147]
	s_add_i32 m0, s43, 0x2000
	s_nop 0
	global_load_lds_dwordx4 v[216:217], off
	v_lshl_add_u64 v[216:217], v[220:221], 0, s[16:17]
	s_mov_b32 m0, s55
	s_nop 0
	global_load_lds_dwordx4 v[216:217], off
	v_lshl_add_u64 v[216:217], v[222:223], 0, s[16:17]
	s_mov_b32 m0, s56
	s_nop 0
	global_load_lds_dwordx4 v[216:217], off
	s_waitcnt vmcnt(8)
	s_waitcnt lgkmcnt(0)
	s_barrier
	s_setprio 1
	s_waitcnt lgkmcnt(0)
	v_mfma_f32_16x16x32_bf16 v[62:65], v[130:133], v[184:187], v[62:65]
	v_mfma_f32_16x16x32_bf16 v[58:61], v[138:141], v[184:187], v[58:61]
	v_mfma_f32_16x16x32_bf16 v[50:53], v[130:133], v[192:195], v[50:53]
	v_mfma_f32_16x16x32_bf16 v[42:45], v[138:141], v[192:195], v[42:45]
	v_mfma_f32_16x16x32_bf16 v[34:37], v[130:133], v[200:203], v[34:37]
	v_mfma_f32_16x16x32_bf16 v[26:29], v[138:141], v[200:203], v[26:29]
	v_mfma_f32_16x16x32_bf16 v[18:21], v[130:133], v[208:211], v[18:21]
	v_mfma_f32_16x16x32_bf16 v[10:13], v[138:141], v[208:211], v[10:13]
	v_mfma_f32_16x16x32_bf16 v[62:65], v[134:137], v[188:191], v[62:65]
	v_mfma_f32_16x16x32_bf16 v[58:61], v[142:145], v[188:191], v[58:61]
	v_mfma_f32_16x16x32_bf16 v[50:53], v[134:137], v[196:199], v[50:53]
	v_mfma_f32_16x16x32_bf16 v[42:45], v[142:145], v[196:199], v[42:45]
	v_mfma_f32_16x16x32_bf16 v[34:37], v[134:137], v[204:207], v[34:37]
	v_mfma_f32_16x16x32_bf16 v[26:29], v[142:145], v[204:207], v[26:29]
	v_mfma_f32_16x16x32_bf16 v[18:21], v[134:137], v[212:215], v[18:21]
	v_mfma_f32_16x16x32_bf16 v[10:13], v[142:145], v[212:215], v[10:13]
	s_setprio 0
	s_setprio 1
	v_mfma_f32_16x16x32_bf16 v[54:57], v[162:165], v[184:187], v[54:57]
	v_mfma_f32_16x16x32_bf16 v[46:49], v[176:179], v[184:187], v[46:49]
	v_mfma_f32_16x16x32_bf16 v[38:41], v[162:165], v[192:195], v[38:41]
	v_mfma_f32_16x16x32_bf16 v[30:33], v[176:179], v[192:195], v[30:33]
	v_mfma_f32_16x16x32_bf16 v[22:25], v[162:165], v[200:203], v[22:25]
	v_mfma_f32_16x16x32_bf16 v[14:17], v[176:179], v[200:203], v[14:17]
	v_mfma_f32_16x16x32_bf16 v[6:9], v[162:165], v[208:211], v[6:9]
	v_mfma_f32_16x16x32_bf16 v[2:5], v[176:179], v[208:211], v[2:5]
	v_mfma_f32_16x16x32_bf16 v[54:57], v[172:175], v[188:191], v[54:57]
	v_mfma_f32_16x16x32_bf16 v[46:49], v[180:183], v[188:191], v[46:49]
	v_mfma_f32_16x16x32_bf16 v[38:41], v[172:175], v[196:199], v[38:41]
	v_mfma_f32_16x16x32_bf16 v[30:33], v[180:183], v[196:199], v[30:33]
	v_mfma_f32_16x16x32_bf16 v[22:25], v[172:175], v[204:207], v[22:25]
	v_mfma_f32_16x16x32_bf16 v[14:17], v[180:183], v[204:207], v[14:17]
	v_mfma_f32_16x16x32_bf16 v[6:9], v[172:175], v[212:215], v[6:9]
	v_mfma_f32_16x16x32_bf16 v[2:5], v[180:183], v[212:215], v[2:5]
	s_setprio 0
	s_barrier
	s_add_i32 s69, s69, 2
	s_add_u32 s2, s2, 0x100
	s_addc_u32 s3, s3, 0
	s_add_u32 s67, s67, 0x100
	s_addc_u32 s68, s68, 0
	s_cmp_gt_u32 s69, 61
	s_cbranch_scc0 .LBB0_1521
	s_and_b64 vcc, exec, s[18:19]
	s_cbranch_vccz .LBB0_1524
	s_barrier

.LBB0_1697:
	ds_read_b128 v[130:133], v238
	ds_read_b128 v[134:137], v238 offset:1024
	ds_read_b128 v[138:141], v238 offset:2048
	ds_read_b128 v[142:145], v238 offset:3072
	ds_read_b128 v[146:149], v239
	ds_read_b128 v[150:153], v239 offset:1024
	ds_read_b128 v[154:157], v239 offset:2048
	ds_read_b128 v[158:161], v239 offset:3072
	s_add_u32 s56, s2, 0x100
	s_addc_u32 s57, s3, 0
	s_cmp_eq_u32 s91, 28
	s_cselect_b32 s61, s49, s57
	s_cselect_b32 s60, s87, s56
	s_cselect_b32 s59, s47, s90
	s_cselect_b32 s58, s88, s89
	v_lshl_add_u64 v[194:195], s[2:3], 0, v[210:211]
	s_add_i32 m0, s55, 0xc000
	ds_read_b128 v[162:165], v240
	ds_read_b128 v[166:169], v240 offset:1024
	ds_read_b128 v[170:173], v240 offset:2048
	ds_read_b128 v[174:177], v240 offset:3072
	ds_read_b128 v[178:181], v240 offset:4096
	ds_read_b128 v[182:185], v240 offset:5120
	ds_read_b128 v[186:189], v240 offset:6144
	ds_read_b128 v[190:193], v240 offset:7168
	global_load_lds_dwordx4 v[194:195], off
	v_lshl_add_u64 v[194:195], s[2:3], 0, v[212:213]
	s_add_i32 m0, s55, 0xe000
	s_nop 0
	global_load_lds_dwordx4 v[194:195], off
	s_waitcnt vmcnt(8)
	s_waitcnt lgkmcnt(0)
	s_barrier
	s_setprio 1
	s_waitcnt lgkmcnt(0)
	v_mfma_i32_16x16x64_i8 v[126:129], v[130:133], v[162:165], v[126:129]
	v_mfma_i32_16x16x64_i8 v[122:125], v[138:141], v[162:165], v[122:125]
	v_mfma_i32_16x16x64_i8 v[118:121], v[130:133], v[170:173], v[118:121]
	v_mfma_i32_16x16x64_i8 v[110:113], v[138:141], v[170:173], v[110:113]
	v_mfma_i32_16x16x64_i8 v[78:81], v[130:133], v[178:181], v[78:81]
	v_mfma_i32_16x16x64_i8 v[30:33], v[138:141], v[178:181], v[30:33]
	v_mfma_i32_16x16x64_i8 v[74:77], v[130:133], v[186:189], v[74:77]
	v_mfma_i32_16x16x64_i8 v[26:29], v[138:141], v[186:189], v[26:29]
	v_mfma_i32_16x16x64_i8 v[126:129], v[134:137], v[166:169], v[126:129]
	v_mfma_i32_16x16x64_i8 v[122:125], v[142:145], v[166:169], v[122:125]
	v_mfma_i32_16x16x64_i8 v[118:121], v[134:137], v[174:177], v[118:121]
	v_mfma_i32_16x16x64_i8 v[110:113], v[142:145], v[174:177], v[110:113]
	v_mfma_i32_16x16x64_i8 v[78:81], v[134:137], v[182:185], v[78:81]
	v_mfma_i32_16x16x64_i8 v[30:33], v[142:145], v[182:185], v[30:33]
	v_mfma_i32_16x16x64_i8 v[74:77], v[134:137], v[190:193], v[74:77]
	v_mfma_i32_16x16x64_i8 v[26:29], v[142:145], v[190:193], v[26:29]
	s_setprio 0
	s_setprio 1
	v_mfma_i32_16x16x64_i8 v[102:105], v[146:149], v[162:165], v[102:105]
	v_mfma_i32_16x16x64_i8 v[98:101], v[154:157], v[162:165], v[98:101]
	v_mfma_i32_16x16x64_i8 v[94:97], v[146:149], v[170:173], v[94:97]
	v_mfma_i32_16x16x64_i8 v[90:93], v[154:157], v[170:173], v[90:93]
	v_mfma_i32_16x16x64_i8 v[70:73], v[146:149], v[178:181], v[70:73]
	v_mfma_i32_16x16x64_i8 v[22:25], v[154:157], v[178:181], v[22:25]
	v_mfma_i32_16x16x64_i8 v[66:69], v[146:149], v[186:189], v[66:69]
	v_mfma_i32_16x16x64_i8 v[18:21], v[154:157], v[186:189], v[18:21]
	v_mfma_i32_16x16x64_i8 v[102:105], v[150:153], v[166:169], v[102:105]
	v_mfma_i32_16x16x64_i8 v[98:101], v[158:161], v[166:169], v[98:101]
	v_mfma_i32_16x16x64_i8 v[94:97], v[150:153], v[174:177], v[94:97]
	v_mfma_i32_16x16x64_i8 v[90:93], v[158:161], v[174:177], v[90:93]
	v_mfma_i32_16x16x64_i8 v[70:73], v[150:153], v[182:185], v[70:73]
	v_mfma_i32_16x16x64_i8 v[22:25], v[158:161], v[182:185], v[22:25]
	v_mfma_i32_16x16x64_i8 v[66:69], v[150:153], v[190:193], v[66:69]
	v_mfma_i32_16x16x64_i8 v[18:21], v[158:161], v[190:193], v[18:21]
	s_setprio 0
	s_barrier
	s_add_i32 s2, s83, s66
	v_lshl_add_u64 v[194:195], s[58:59], 0, v[206:207]
	s_mov_b32 m0, s2
	ds_read_b128 v[162:165], v240 offset:16384
	ds_read_b128 v[166:169], v240 offset:17408
	ds_read_b128 v[170:173], v240 offset:18432
	ds_read_b128 v[174:177], v240 offset:19456
	ds_read_b128 v[178:181], v240 offset:20480
	ds_read_b128 v[182:185], v240 offset:21504
	ds_read_b128 v[186:189], v240 offset:22528
	ds_read_b128 v[190:193], v240 offset:23552
	global_load_lds_dwordx4 v[194:195], off
	s_add_i32 m0, s2, 0x2000
	s_add_u32 s2, s58, 0x80000
	v_lshl_add_u64 v[196:197], s[58:59], 0, v[202:203]
	s_addc_u32 s3, s59, 0
	s_add_i32 s43, s84, s66
	global_load_lds_dwordx4 v[196:197], off
	v_lshl_add_u64 v[198:199], s[2:3], 0, v[206:207]
	s_mov_b32 m0, s43
	v_lshl_add_u64 v[200:201], s[60:61], 0, v[204:205]
	global_load_lds_dwordx4 v[198:199], off
	v_lshl_add_u64 v[198:199], s[2:3], 0, v[202:203]
	s_add_i32 m0, s43, 0x2000
	s_nop 0
	global_load_lds_dwordx4 v[198:199], off
	v_lshl_add_u64 v[198:199], s[60:61], 0, v[208:209]
	s_mov_b32 m0, s55
	s_nop 0
	global_load_lds_dwordx4 v[198:199], off
	s_mov_b32 m0, s68
	s_nop 0
	global_load_lds_dwordx4 v[200:201], off
	s_waitcnt vmcnt(8)
	s_waitcnt lgkmcnt(0)
	s_barrier
	s_nop 0
	s_setprio 1
	s_waitcnt lgkmcnt(0)
	v_mfma_i32_16x16x64_i8 v[62:65], v[130:133], v[162:165], v[62:65]
	v_mfma_i32_16x16x64_i8 v[14:17], v[138:141], v[162:165], v[14:17]
	v_mfma_i32_16x16x64_i8 v[58:61], v[130:133], v[170:173], v[58:61]
	v_mfma_i32_16x16x64_i8 v[10:13], v[138:141], v[170:173], v[10:13]
	v_mfma_i32_16x16x64_i8 v[114:117], v[130:133], v[178:181], v[114:117]
	v_mfma_i32_16x16x64_i8 v[106:109], v[138:141], v[178:181], v[106:109]
	v_mfma_i32_16x16x64_i8 v[86:89], v[130:133], v[186:189], v[86:89]
	v_mfma_i32_16x16x64_i8 v[82:85], v[138:141], v[186:189], v[82:85]
	v_mfma_i32_16x16x64_i8 v[62:65], v[134:137], v[166:169], v[62:65]
	v_mfma_i32_16x16x64_i8 v[14:17], v[142:145], v[166:169], v[14:17]
	v_mfma_i32_16x16x64_i8 v[58:61], v[134:137], v[174:177], v[58:61]
	v_mfma_i32_16x16x64_i8 v[10:13], v[142:145], v[174:177], v[10:13]
	v_mfma_i32_16x16x64_i8 v[114:117], v[134:137], v[182:185], v[114:117]
	v_mfma_i32_16x16x64_i8 v[106:109], v[142:145], v[182:185], v[106:109]
	v_mfma_i32_16x16x64_i8 v[86:89], v[134:137], v[190:193], v[86:89]
	v_mfma_i32_16x16x64_i8 v[82:85], v[142:145], v[190:193], v[82:85]
	s_setprio 0
	s_setprio 1
	v_mfma_i32_16x16x64_i8 v[50:53], v[146:149], v[162:165], v[50:53]
	v_mfma_i32_16x16x64_i8 v[6:9], v[154:157], v[162:165], v[6:9]
	v_mfma_i32_16x16x64_i8 v[42:45], v[146:149], v[170:173], v[42:45]
	v_mfma_i32_16x16x64_i8 v[2:5], v[154:157], v[170:173], v[2:5]
	v_mfma_i32_16x16x64_i8 v[54:57], v[146:149], v[178:181], v[54:57]
	v_mfma_i32_16x16x64_i8 v[46:49], v[154:157], v[178:181], v[46:49]
	v_mfma_i32_16x16x64_i8 v[38:41], v[146:149], v[186:189], v[38:41]
	v_mfma_i32_16x16x64_i8 v[34:37], v[154:157], v[186:189], v[34:37]
	v_mfma_i32_16x16x64_i8 v[50:53], v[150:153], v[166:169], v[50:53]
	v_mfma_i32_16x16x64_i8 v[6:9], v[158:161], v[166:169], v[6:9]
	v_mfma_i32_16x16x64_i8 v[42:45], v[150:153], v[174:177], v[42:45]
	v_mfma_i32_16x16x64_i8 v[2:5], v[158:161], v[174:177], v[2:5]
	v_mfma_i32_16x16x64_i8 v[54:57], v[150:153], v[182:185], v[54:57]
	v_mfma_i32_16x16x64_i8 v[46:49], v[158:161], v[182:185], v[46:49]
	v_mfma_i32_16x16x64_i8 v[38:41], v[150:153], v[190:193], v[38:41]
	v_mfma_i32_16x16x64_i8 v[34:37], v[158:161], v[190:193], v[34:37]
	s_setprio 0
	s_barrier
	s_add_i32 s43, 0, 0x18000
	s_add_i32 s92, 0, 0x1c000
	v_add_u32_e32 v142, s43, v237
	v_add_u32_e32 v158, s92, v237
	ds_read_b128 v[130:133], v142
	ds_read_b128 v[134:137], v142 offset:1024
	ds_read_b128 v[138:141], v142 offset:2048
	ds_read_b128 v[142:145], v142 offset:3072
	ds_read_b128 v[146:149], v158
	ds_read_b128 v[150:153], v158 offset:1024
	ds_read_b128 v[154:157], v158 offset:2048
	ds_read_b128 v[158:161], v158 offset:3072
	s_add_u32 s2, s60, 0x4000
	s_addc_u32 s3, s61, 0
	s_mov_b32 m0, s69
	v_lshl_add_u64 v[220:221], s[2:3], 0, v[208:209]
	ds_read_b128 v[162:165], v240 offset:32768
	ds_read_b128 v[166:169], v240 offset:33792
	ds_read_b128 v[170:173], v240 offset:34816
	ds_read_b128 v[174:177], v240 offset:35840
	ds_read_b128 v[178:181], v240 offset:36864
	ds_read_b128 v[182:185], v240 offset:37888
	ds_read_b128 v[186:189], v240 offset:38912
	ds_read_b128 v[190:193], v240 offset:39936
	global_load_lds_dwordx4 v[220:221], off
	v_lshl_add_u64 v[220:221], s[2:3], 0, v[204:205]
	s_mov_b32 m0, s70
	s_nop 0
	global_load_lds_dwordx4 v[220:221], off
	s_waitcnt vmcnt(8)
	s_waitcnt lgkmcnt(0)
	s_barrier
	s_nop 0
	s_setprio 1
	s_waitcnt lgkmcnt(0)
	v_mfma_i32_16x16x64_i8 v[126:129], v[130:133], v[162:165], v[126:129]
	v_mfma_i32_16x16x64_i8 v[122:125], v[138:141], v[162:165], v[122:125]
	v_mfma_i32_16x16x64_i8 v[118:121], v[130:133], v[170:173], v[118:121]
	v_mfma_i32_16x16x64_i8 v[110:113], v[138:141], v[170:173], v[110:113]
	v_mfma_i32_16x16x64_i8 v[78:81], v[130:133], v[178:181], v[78:81]
	v_mfma_i32_16x16x64_i8 v[30:33], v[138:141], v[178:181], v[30:33]
	v_mfma_i32_16x16x64_i8 v[74:77], v[130:133], v[186:189], v[74:77]
	v_mfma_i32_16x16x64_i8 v[26:29], v[138:141], v[186:189], v[26:29]
	v_mfma_i32_16x16x64_i8 v[126:129], v[134:137], v[166:169], v[126:129]
	v_mfma_i32_16x16x64_i8 v[122:125], v[142:145], v[166:169], v[122:125]
	v_mfma_i32_16x16x64_i8 v[118:121], v[134:137], v[174:177], v[118:121]
	v_mfma_i32_16x16x64_i8 v[110:113], v[142:145], v[174:177], v[110:113]
	v_mfma_i32_16x16x64_i8 v[78:81], v[134:137], v[182:185], v[78:81]
	v_mfma_i32_16x16x64_i8 v[30:33], v[142:145], v[182:185], v[30:33]
	v_mfma_i32_16x16x64_i8 v[74:77], v[134:137], v[190:193], v[74:77]
	v_mfma_i32_16x16x64_i8 v[26:29], v[142:145], v[190:193], v[26:29]
	s_setprio 0
	s_setprio 1
	v_mfma_i32_16x16x64_i8 v[102:105], v[146:149], v[162:165], v[102:105]
	v_mfma_i32_16x16x64_i8 v[98:101], v[154:157], v[162:165], v[98:101]
	v_mfma_i32_16x16x64_i8 v[94:97], v[146:149], v[170:173], v[94:97]
	v_mfma_i32_16x16x64_i8 v[90:93], v[154:157], v[170:173], v[90:93]
	v_mfma_i32_16x16x64_i8 v[70:73], v[146:149], v[178:181], v[70:73]
	v_mfma_i32_16x16x64_i8 v[22:25], v[154:157], v[178:181], v[22:25]
	v_mfma_i32_16x16x64_i8 v[66:69], v[146:149], v[186:189], v[66:69]
	v_mfma_i32_16x16x64_i8 v[18:21], v[154:157], v[186:189], v[18:21]
	v_mfma_i32_16x16x64_i8 v[102:105], v[150:153], v[166:169], v[102:105]
	v_mfma_i32_16x16x64_i8 v[98:101], v[158:161], v[166:169], v[98:101]
	v_mfma_i32_16x16x64_i8 v[94:97], v[150:153], v[174:177], v[94:97]
	v_mfma_i32_16x16x64_i8 v[90:93], v[158:161], v[174:177], v[90:93]
	v_mfma_i32_16x16x64_i8 v[70:73], v[150:153], v[182:185], v[70:73]
	v_mfma_i32_16x16x64_i8 v[22:25], v[158:161], v[182:185], v[22:25]
	v_mfma_i32_16x16x64_i8 v[66:69], v[150:153], v[190:193], v[66:69]
	v_mfma_i32_16x16x64_i8 v[18:21], v[158:161], v[190:193], v[18:21]
	s_setprio 0
	s_barrier
	s_add_i32 s2, s43, s66
	v_lshl_add_u64 v[194:195], v[194:195], 0, s[36:37]
	s_mov_b32 m0, s2
	ds_read_b128 v[162:165], v240 offset:49152
	ds_read_b128 v[166:169], v240 offset:50176
	ds_read_b128 v[170:173], v240 offset:51200
	ds_read_b128 v[174:177], v240 offset:52224
	ds_read_b128 v[178:181], v240 offset:53248
	ds_read_b128 v[182:185], v240 offset:54272
	ds_read_b128 v[186:189], v240 offset:55296
	ds_read_b128 v[190:193], v240 offset:56320
	global_load_lds_dwordx4 v[194:195], off
	s_add_i32 m0, s2, 0x2000
	s_add_u32 s2, s58, 0x80080
	v_lshl_add_u64 v[194:195], v[196:197], 0, s[36:37]
	s_addc_u32 s3, s59, 0
	s_add_i32 s43, s92, s66
	global_load_lds_dwordx4 v[194:195], off
	v_lshl_add_u64 v[194:195], s[2:3], 0, v[206:207]
	s_mov_b32 m0, s43
	s_nop 0
	global_load_lds_dwordx4 v[194:195], off
	v_lshl_add_u64 v[194:195], s[2:3], 0, v[202:203]
	s_add_i32 m0, s43, 0x2000
	s_nop 0
	global_load_lds_dwordx4 v[194:195], off
	v_lshl_add_u64 v[194:195], v[198:199], 0, s[36:37]
	s_mov_b32 m0, s77
	s_nop 0
	global_load_lds_dwordx4 v[194:195], off
	v_lshl_add_u64 v[194:195], v[200:201], 0, s[36:37]
	s_mov_b32 m0, s78
	s_nop 0
	global_load_lds_dwordx4 v[194:195], off
	s_waitcnt vmcnt(8)
	s_waitcnt lgkmcnt(0)
	s_barrier
	s_setprio 1
	s_waitcnt lgkmcnt(0)
	v_mfma_i32_16x16x64_i8 v[62:65], v[130:133], v[162:165], v[62:65]
	v_mfma_i32_16x16x64_i8 v[14:17], v[138:141], v[162:165], v[14:17]
	v_mfma_i32_16x16x64_i8 v[58:61], v[130:133], v[170:173], v[58:61]
	v_mfma_i32_16x16x64_i8 v[10:13], v[138:141], v[170:173], v[10:13]
	v_mfma_i32_16x16x64_i8 v[114:117], v[130:133], v[178:181], v[114:117]
	v_mfma_i32_16x16x64_i8 v[106:109], v[138:141], v[178:181], v[106:109]
	v_mfma_i32_16x16x64_i8 v[86:89], v[130:133], v[186:189], v[86:89]
	v_mfma_i32_16x16x64_i8 v[82:85], v[138:141], v[186:189], v[82:85]
	v_mfma_i32_16x16x64_i8 v[62:65], v[134:137], v[166:169], v[62:65]
	v_mfma_i32_16x16x64_i8 v[14:17], v[142:145], v[166:169], v[14:17]
	v_mfma_i32_16x16x64_i8 v[58:61], v[134:137], v[174:177], v[58:61]
	v_mfma_i32_16x16x64_i8 v[10:13], v[142:145], v[174:177], v[10:13]
	v_mfma_i32_16x16x64_i8 v[114:117], v[134:137], v[182:185], v[114:117]
	v_mfma_i32_16x16x64_i8 v[106:109], v[142:145], v[182:185], v[106:109]
	v_mfma_i32_16x16x64_i8 v[86:89], v[134:137], v[190:193], v[86:89]
	v_mfma_i32_16x16x64_i8 v[82:85], v[142:145], v[190:193], v[82:85]
	s_setprio 0
	s_setprio 1
	v_mfma_i32_16x16x64_i8 v[50:53], v[146:149], v[162:165], v[50:53]
	v_mfma_i32_16x16x64_i8 v[6:9], v[154:157], v[162:165], v[6:9]
	v_mfma_i32_16x16x64_i8 v[42:45], v[146:149], v[170:173], v[42:45]
	v_mfma_i32_16x16x64_i8 v[2:5], v[154:157], v[170:173], v[2:5]
	v_mfma_i32_16x16x64_i8 v[54:57], v[146:149], v[178:181], v[54:57]
	v_mfma_i32_16x16x64_i8 v[46:49], v[154:157], v[178:181], v[46:49]
	v_mfma_i32_16x16x64_i8 v[38:41], v[146:149], v[186:189], v[38:41]
	v_mfma_i32_16x16x64_i8 v[34:37], v[154:157], v[186:189], v[34:37]
	v_mfma_i32_16x16x64_i8 v[50:53], v[150:153], v[166:169], v[50:53]
	v_mfma_i32_16x16x64_i8 v[6:9], v[158:161], v[166:169], v[6:9]
	v_mfma_i32_16x16x64_i8 v[42:45], v[150:153], v[174:177], v[42:45]
	v_mfma_i32_16x16x64_i8 v[2:5], v[158:161], v[174:177], v[2:5]
	v_mfma_i32_16x16x64_i8 v[54:57], v[150:153], v[182:185], v[54:57]
	v_mfma_i32_16x16x64_i8 v[46:49], v[158:161], v[182:185], v[46:49]
	v_mfma_i32_16x16x64_i8 v[38:41], v[150:153], v[190:193], v[38:41]
	v_mfma_i32_16x16x64_i8 v[34:37], v[158:161], v[190:193], v[34:37]
	s_setprio 0
	s_barrier
	s_add_i32 s91, s91, 2
	s_add_u32 s89, s89, 0x100
	s_addc_u32 s90, s90, 0
	s_cmp_gt_u32 s91, 29
	s_mov_b64 s[2:3], s[56:57]
	s_cbranch_scc0 .LBB0_1697
	s_and_b64 vcc, exec, s[38:39]
	s_cbranch_vccz .LBB0_1700
	s_barrier

.LBB0_1951:
	ds_read_b128 v[130:133], v167
	ds_read_b128 v[134:137], v167 offset:1024
	ds_read_b128 v[138:141], v167 offset:2048
	ds_read_b128 v[142:145], v167 offset:3072
	ds_read_b128 v[170:173], v168
	ds_read_b128 v[174:177], v168 offset:1024
	ds_read_b128 v[178:181], v168 offset:2048
	ds_read_b128 v[182:185], v168 offset:3072
	s_add_u32 s38, s36, 0x100
	s_addc_u32 s39, s37, 0
	s_cmpk_eq_i32 s77, 0x52
	s_cselect_b32 s47, s3, s39
	s_cselect_b32 s46, s2, s38
	s_cselect_b32 s45, s35, s76
	s_cselect_b32 s44, s34, s75
	v_lshl_add_u64 v[162:163], s[36:37], 0, v[154:155]
	s_add_i32 m0, s52, 0xc000
	ds_read_b128 v[186:189], v169
	ds_read_b128 v[190:193], v169 offset:1024
	ds_read_b128 v[194:197], v169 offset:2048
	ds_read_b128 v[198:201], v169 offset:3072
	ds_read_b128 v[202:205], v169 offset:4096
	ds_read_b128 v[206:209], v169 offset:5120
	ds_read_b128 v[210:213], v169 offset:6144
	ds_read_b128 v[214:217], v169 offset:7168
	global_load_lds_dwordx4 v[162:163], off
	v_lshl_add_u64 v[162:163], s[36:37], 0, v[156:157]
	s_add_i32 m0, s52, 0xe000
	s_nop 0
	global_load_lds_dwordx4 v[162:163], off
	s_waitcnt vmcnt(8)
	s_waitcnt lgkmcnt(0)
	s_barrier
	s_setprio 1
	s_waitcnt lgkmcnt(0)
	v_mfma_i32_16x16x64_i8 v[126:129], v[130:133], v[186:189], v[126:129]
	v_mfma_i32_16x16x64_i8 v[122:125], v[138:141], v[186:189], v[122:125]
	v_mfma_i32_16x16x64_i8 v[110:113], v[130:133], v[194:197], v[110:113]
	v_mfma_i32_16x16x64_i8 v[106:109], v[138:141], v[194:197], v[106:109]
	v_mfma_i32_16x16x64_i8 v[94:97], v[130:133], v[202:205], v[94:97]
	v_mfma_i32_16x16x64_i8 v[90:93], v[138:141], v[202:205], v[90:93]
	v_mfma_i32_16x16x64_i8 v[78:81], v[130:133], v[210:213], v[78:81]
	v_mfma_i32_16x16x64_i8 v[74:77], v[138:141], v[210:213], v[74:77]
	v_mfma_i32_16x16x64_i8 v[126:129], v[134:137], v[190:193], v[126:129]
	v_mfma_i32_16x16x64_i8 v[122:125], v[142:145], v[190:193], v[122:125]
	v_mfma_i32_16x16x64_i8 v[110:113], v[134:137], v[198:201], v[110:113]
	v_mfma_i32_16x16x64_i8 v[106:109], v[142:145], v[198:201], v[106:109]
	v_mfma_i32_16x16x64_i8 v[94:97], v[134:137], v[206:209], v[94:97]
	v_mfma_i32_16x16x64_i8 v[90:93], v[142:145], v[206:209], v[90:93]
	v_mfma_i32_16x16x64_i8 v[78:81], v[134:137], v[214:217], v[78:81]
	v_mfma_i32_16x16x64_i8 v[74:77], v[142:145], v[214:217], v[74:77]
	s_setprio 0
	s_setprio 1
	v_mfma_i32_16x16x64_i8 v[118:121], v[170:173], v[186:189], v[118:121]
	v_mfma_i32_16x16x64_i8 v[114:117], v[178:181], v[186:189], v[114:117]
	v_mfma_i32_16x16x64_i8 v[102:105], v[170:173], v[194:197], v[102:105]
	v_mfma_i32_16x16x64_i8 v[98:101], v[178:181], v[194:197], v[98:101]
	v_mfma_i32_16x16x64_i8 v[86:89], v[170:173], v[202:205], v[86:89]
	v_mfma_i32_16x16x64_i8 v[82:85], v[178:181], v[202:205], v[82:85]
	v_mfma_i32_16x16x64_i8 v[70:73], v[170:173], v[210:213], v[70:73]
	v_mfma_i32_16x16x64_i8 v[66:69], v[178:181], v[210:213], v[66:69]
	v_mfma_i32_16x16x64_i8 v[118:121], v[174:177], v[190:193], v[118:121]
	v_mfma_i32_16x16x64_i8 v[114:117], v[182:185], v[190:193], v[114:117]
	v_mfma_i32_16x16x64_i8 v[102:105], v[174:177], v[198:201], v[102:105]
	v_mfma_i32_16x16x64_i8 v[98:101], v[182:185], v[198:201], v[98:101]
	v_mfma_i32_16x16x64_i8 v[86:89], v[174:177], v[206:209], v[86:89]
	v_mfma_i32_16x16x64_i8 v[82:85], v[182:185], v[206:209], v[82:85]
	v_mfma_i32_16x16x64_i8 v[70:73], v[174:177], v[214:217], v[70:73]
	v_mfma_i32_16x16x64_i8 v[66:69], v[182:185], v[214:217], v[66:69]
	s_setprio 0
	s_barrier
	s_add_i32 s36, s61, s51
	v_lshl_add_u64 v[162:163], s[44:45], 0, v[150:151]
	s_mov_b32 m0, s36
	ds_read_b128 v[186:189], v169 offset:16384
	ds_read_b128 v[190:193], v169 offset:17408
	ds_read_b128 v[194:197], v169 offset:18432
	ds_read_b128 v[198:201], v169 offset:19456
	ds_read_b128 v[202:205], v169 offset:20480
	ds_read_b128 v[206:209], v169 offset:21504
	ds_read_b128 v[210:213], v169 offset:22528
	ds_read_b128 v[214:217], v169 offset:23552
	global_load_lds_dwordx4 v[162:163], off
	s_add_i32 m0, s36, 0x2000
	s_add_u32 s36, s44, 0x158000
	v_lshl_add_u64 v[218:219], s[44:45], 0, v[146:147]
	s_addc_u32 s37, s45, 0
	s_add_i32 s78, s62, s51
	global_load_lds_dwordx4 v[218:219], off
	v_lshl_add_u64 v[220:221], s[36:37], 0, v[150:151]
	s_mov_b32 m0, s78
	v_lshl_add_u64 v[222:223], s[46:47], 0, v[148:149]
	global_load_lds_dwordx4 v[220:221], off
	v_lshl_add_u64 v[220:221], s[36:37], 0, v[146:147]
	s_add_i32 m0, s78, 0x2000
	s_nop 0
	global_load_lds_dwordx4 v[220:221], off
	v_lshl_add_u64 v[220:221], s[46:47], 0, v[152:153]
	s_mov_b32 m0, s52
	s_nop 0
	global_load_lds_dwordx4 v[220:221], off
	s_mov_b32 m0, s53
	s_nop 0
	global_load_lds_dwordx4 v[222:223], off
	s_waitcnt vmcnt(8)
	s_waitcnt lgkmcnt(0)
	s_barrier
	s_nop 0
	s_setprio 1
	s_waitcnt lgkmcnt(0)
	v_mfma_i32_16x16x64_i8 v[62:65], v[130:133], v[186:189], v[62:65]
	v_mfma_i32_16x16x64_i8 v[58:61], v[138:141], v[186:189], v[58:61]
	v_mfma_i32_16x16x64_i8 v[46:49], v[130:133], v[194:197], v[46:49]
	v_mfma_i32_16x16x64_i8 v[42:45], v[138:141], v[194:197], v[42:45]
	v_mfma_i32_16x16x64_i8 v[30:33], v[130:133], v[202:205], v[30:33]
	v_mfma_i32_16x16x64_i8 v[26:29], v[138:141], v[202:205], v[26:29]
	v_mfma_i32_16x16x64_i8 v[14:17], v[130:133], v[210:213], v[14:17]
	v_mfma_i32_16x16x64_i8 v[10:13], v[138:141], v[210:213], v[10:13]
	v_mfma_i32_16x16x64_i8 v[62:65], v[134:137], v[190:193], v[62:65]
	v_mfma_i32_16x16x64_i8 v[58:61], v[142:145], v[190:193], v[58:61]
	v_mfma_i32_16x16x64_i8 v[46:49], v[134:137], v[198:201], v[46:49]
	v_mfma_i32_16x16x64_i8 v[42:45], v[142:145], v[198:201], v[42:45]
	v_mfma_i32_16x16x64_i8 v[30:33], v[134:137], v[206:209], v[30:33]
	v_mfma_i32_16x16x64_i8 v[26:29], v[142:145], v[206:209], v[26:29]
	v_mfma_i32_16x16x64_i8 v[14:17], v[134:137], v[214:217], v[14:17]
	v_mfma_i32_16x16x64_i8 v[10:13], v[142:145], v[214:217], v[10:13]
	s_setprio 0
	s_setprio 1
	v_mfma_i32_16x16x64_i8 v[54:57], v[170:173], v[186:189], v[54:57]
	v_mfma_i32_16x16x64_i8 v[50:53], v[178:181], v[186:189], v[50:53]
	v_mfma_i32_16x16x64_i8 v[38:41], v[170:173], v[194:197], v[38:41]
	v_mfma_i32_16x16x64_i8 v[34:37], v[178:181], v[194:197], v[34:37]
	v_mfma_i32_16x16x64_i8 v[22:25], v[170:173], v[202:205], v[22:25]
	v_mfma_i32_16x16x64_i8 v[18:21], v[178:181], v[202:205], v[18:21]
	v_mfma_i32_16x16x64_i8 v[6:9], v[170:173], v[210:213], v[6:9]
	v_mfma_i32_16x16x64_i8 v[2:5], v[178:181], v[210:213], v[2:5]
	v_mfma_i32_16x16x64_i8 v[54:57], v[174:177], v[190:193], v[54:57]
	v_mfma_i32_16x16x64_i8 v[50:53], v[182:185], v[190:193], v[50:53]
	v_mfma_i32_16x16x64_i8 v[38:41], v[174:177], v[198:201], v[38:41]
	v_mfma_i32_16x16x64_i8 v[34:37], v[182:185], v[198:201], v[34:37]
	v_mfma_i32_16x16x64_i8 v[22:25], v[174:177], v[206:209], v[22:25]
	v_mfma_i32_16x16x64_i8 v[18:21], v[182:185], v[206:209], v[18:21]
	v_mfma_i32_16x16x64_i8 v[6:9], v[174:177], v[214:217], v[6:9]
	v_mfma_i32_16x16x64_i8 v[2:5], v[182:185], v[214:217], v[2:5]
	s_setprio 0
	s_barrier
	s_add_i32 s78, 0, 0x18000
	s_add_i32 s79, 0, 0x1c000
	v_add_u32_e32 v142, s78, v166
	v_add_u32_e32 v182, s79, v166
	ds_read_b128 v[130:133], v142
	ds_read_b128 v[134:137], v142 offset:1024
	ds_read_b128 v[138:141], v142 offset:2048
	ds_read_b128 v[142:145], v142 offset:3072
	ds_read_b128 v[170:173], v182
	ds_read_b128 v[174:177], v182 offset:1024
	ds_read_b128 v[178:181], v182 offset:2048
	ds_read_b128 v[182:185], v182 offset:3072
	s_add_u32 s36, s46, 0x158000
	s_addc_u32 s37, s47, 0
	s_mov_b32 m0, s54
	v_lshl_add_u64 v[224:225], s[36:37], 0, v[152:153]
	ds_read_b128 v[186:189], v169 offset:32768
	ds_read_b128 v[190:193], v169 offset:33792
	ds_read_b128 v[194:197], v169 offset:34816
	ds_read_b128 v[198:201], v169 offset:35840
	ds_read_b128 v[202:205], v169 offset:36864
	ds_read_b128 v[206:209], v169 offset:37888
	ds_read_b128 v[210:213], v169 offset:38912
	ds_read_b128 v[214:217], v169 offset:39936
	global_load_lds_dwordx4 v[224:225], off
	v_lshl_add_u64 v[224:225], s[36:37], 0, v[148:149]
	s_mov_b32 m0, s55
	s_nop 0
	global_load_lds_dwordx4 v[224:225], off
	s_waitcnt vmcnt(8)
	s_waitcnt lgkmcnt(0)
	s_barrier
	s_nop 0
	s_setprio 1
	s_waitcnt lgkmcnt(0)
	v_mfma_i32_16x16x64_i8 v[126:129], v[130:133], v[186:189], v[126:129]
	v_mfma_i32_16x16x64_i8 v[122:125], v[138:141], v[186:189], v[122:125]
	v_mfma_i32_16x16x64_i8 v[110:113], v[130:133], v[194:197], v[110:113]
	v_mfma_i32_16x16x64_i8 v[106:109], v[138:141], v[194:197], v[106:109]
	v_mfma_i32_16x16x64_i8 v[94:97], v[130:133], v[202:205], v[94:97]
	v_mfma_i32_16x16x64_i8 v[90:93], v[138:141], v[202:205], v[90:93]
	v_mfma_i32_16x16x64_i8 v[78:81], v[130:133], v[210:213], v[78:81]
	v_mfma_i32_16x16x64_i8 v[74:77], v[138:141], v[210:213], v[74:77]
	v_mfma_i32_16x16x64_i8 v[126:129], v[134:137], v[190:193], v[126:129]
	v_mfma_i32_16x16x64_i8 v[122:125], v[142:145], v[190:193], v[122:125]
	v_mfma_i32_16x16x64_i8 v[110:113], v[134:137], v[198:201], v[110:113]
	v_mfma_i32_16x16x64_i8 v[106:109], v[142:145], v[198:201], v[106:109]
	v_mfma_i32_16x16x64_i8 v[94:97], v[134:137], v[206:209], v[94:97]
	v_mfma_i32_16x16x64_i8 v[90:93], v[142:145], v[206:209], v[90:93]
	v_mfma_i32_16x16x64_i8 v[78:81], v[134:137], v[214:217], v[78:81]
	v_mfma_i32_16x16x64_i8 v[74:77], v[142:145], v[214:217], v[74:77]
	s_setprio 0
	s_setprio 1
	v_mfma_i32_16x16x64_i8 v[118:121], v[170:173], v[186:189], v[118:121]
	v_mfma_i32_16x16x64_i8 v[114:117], v[178:181], v[186:189], v[114:117]
	v_mfma_i32_16x16x64_i8 v[102:105], v[170:173], v[194:197], v[102:105]
	v_mfma_i32_16x16x64_i8 v[98:101], v[178:181], v[194:197], v[98:101]
	v_mfma_i32_16x16x64_i8 v[86:89], v[170:173], v[202:205], v[86:89]
	v_mfma_i32_16x16x64_i8 v[82:85], v[178:181], v[202:205], v[82:85]
	v_mfma_i32_16x16x64_i8 v[70:73], v[170:173], v[210:213], v[70:73]
	v_mfma_i32_16x16x64_i8 v[66:69], v[178:181], v[210:213], v[66:69]
	v_mfma_i32_16x16x64_i8 v[118:121], v[174:177], v[190:193], v[118:121]
	v_mfma_i32_16x16x64_i8 v[114:117], v[182:185], v[190:193], v[114:117]
	v_mfma_i32_16x16x64_i8 v[102:105], v[174:177], v[198:201], v[102:105]
	v_mfma_i32_16x16x64_i8 v[98:101], v[182:185], v[198:201], v[98:101]
	v_mfma_i32_16x16x64_i8 v[86:89], v[174:177], v[206:209], v[86:89]
	v_mfma_i32_16x16x64_i8 v[82:85], v[182:185], v[206:209], v[82:85]
	v_mfma_i32_16x16x64_i8 v[70:73], v[174:177], v[214:217], v[70:73]
	v_mfma_i32_16x16x64_i8 v[66:69], v[182:185], v[214:217], v[66:69]
	s_setprio 0
	s_barrier
	s_add_i32 s36, s78, s51
	v_lshl_add_u64 v[162:163], v[162:163], 0, s[14:15]
	s_mov_b32 m0, s36
	ds_read_b128 v[186:189], v169 offset:49152
	ds_read_b128 v[190:193], v169 offset:50176
	ds_read_b128 v[194:197], v169 offset:51200
	ds_read_b128 v[198:201], v169 offset:52224
	ds_read_b128 v[202:205], v169 offset:53248
	ds_read_b128 v[206:209], v169 offset:54272
	ds_read_b128 v[210:213], v169 offset:55296
	ds_read_b128 v[214:217], v169 offset:56320
	global_load_lds_dwordx4 v[162:163], off
	s_add_i32 m0, s36, 0x2000
	s_add_u32 s36, s44, 0x158080
	v_lshl_add_u64 v[162:163], v[218:219], 0, s[14:15]
	s_addc_u32 s37, s45, 0
	s_add_i32 s44, s79, s51
	global_load_lds_dwordx4 v[162:163], off
	v_lshl_add_u64 v[162:163], s[36:37], 0, v[150:151]
	s_mov_b32 m0, s44
	s_nop 0
	global_load_lds_dwordx4 v[162:163], off
	v_lshl_add_u64 v[162:163], s[36:37], 0, v[146:147]
	s_add_i32 m0, s44, 0x2000
	s_nop 0
	global_load_lds_dwordx4 v[162:163], off
	v_lshl_add_u64 v[162:163], v[220:221], 0, s[14:15]
	s_mov_b32 m0, s59
	s_nop 0
	global_load_lds_dwordx4 v[162:163], off
	v_lshl_add_u64 v[162:163], v[222:223], 0, s[14:15]
	s_mov_b32 m0, s60
	s_nop 0
	global_load_lds_dwordx4 v[162:163], off
	s_waitcnt vmcnt(8)
	s_waitcnt lgkmcnt(0)
	s_barrier
	s_setprio 1
	s_waitcnt lgkmcnt(0)
	v_mfma_i32_16x16x64_i8 v[62:65], v[130:133], v[186:189], v[62:65]
	v_mfma_i32_16x16x64_i8 v[58:61], v[138:141], v[186:189], v[58:61]
	v_mfma_i32_16x16x64_i8 v[46:49], v[130:133], v[194:197], v[46:49]
	v_mfma_i32_16x16x64_i8 v[42:45], v[138:141], v[194:197], v[42:45]
	v_mfma_i32_16x16x64_i8 v[30:33], v[130:133], v[202:205], v[30:33]
	v_mfma_i32_16x16x64_i8 v[26:29], v[138:141], v[202:205], v[26:29]
	v_mfma_i32_16x16x64_i8 v[14:17], v[130:133], v[210:213], v[14:17]
	v_mfma_i32_16x16x64_i8 v[10:13], v[138:141], v[210:213], v[10:13]
	v_mfma_i32_16x16x64_i8 v[62:65], v[134:137], v[190:193], v[62:65]
	v_mfma_i32_16x16x64_i8 v[58:61], v[142:145], v[190:193], v[58:61]
	v_mfma_i32_16x16x64_i8 v[46:49], v[134:137], v[198:201], v[46:49]
	v_mfma_i32_16x16x64_i8 v[42:45], v[142:145], v[198:201], v[42:45]
	v_mfma_i32_16x16x64_i8 v[30:33], v[134:137], v[206:209], v[30:33]
	v_mfma_i32_16x16x64_i8 v[26:29], v[142:145], v[206:209], v[26:29]
	v_mfma_i32_16x16x64_i8 v[14:17], v[134:137], v[214:217], v[14:17]
	v_mfma_i32_16x16x64_i8 v[10:13], v[142:145], v[214:217], v[10:13]
	s_setprio 0
	s_setprio 1
	v_mfma_i32_16x16x64_i8 v[54:57], v[170:173], v[186:189], v[54:57]
	v_mfma_i32_16x16x64_i8 v[50:53], v[178:181], v[186:189], v[50:53]
	v_mfma_i32_16x16x64_i8 v[38:41], v[170:173], v[194:197], v[38:41]
	v_mfma_i32_16x16x64_i8 v[34:37], v[178:181], v[194:197], v[34:37]
	v_mfma_i32_16x16x64_i8 v[22:25], v[170:173], v[202:205], v[22:25]
	v_mfma_i32_16x16x64_i8 v[18:21], v[178:181], v[202:205], v[18:21]
	v_mfma_i32_16x16x64_i8 v[6:9], v[170:173], v[210:213], v[6:9]
	v_mfma_i32_16x16x64_i8 v[2:5], v[178:181], v[210:213], v[2:5]
	v_mfma_i32_16x16x64_i8 v[54:57], v[174:177], v[190:193], v[54:57]
	v_mfma_i32_16x16x64_i8 v[50:53], v[182:185], v[190:193], v[50:53]
	v_mfma_i32_16x16x64_i8 v[38:41], v[174:177], v[198:201], v[38:41]
	v_mfma_i32_16x16x64_i8 v[34:37], v[182:185], v[198:201], v[34:37]
	v_mfma_i32_16x16x64_i8 v[22:25], v[174:177], v[206:209], v[22:25]
	v_mfma_i32_16x16x64_i8 v[18:21], v[182:185], v[206:209], v[18:21]
	v_mfma_i32_16x16x64_i8 v[6:9], v[174:177], v[214:217], v[6:9]
	v_mfma_i32_16x16x64_i8 v[2:5], v[182:185], v[214:217], v[2:5]
	s_setprio 0
	s_barrier
	s_add_i32 s77, s77, 2
	s_add_u32 s75, s75, 0x100
	s_addc_u32 s76, s76, 0
	s_cmpk_gt_u32 s77, 0x53
	s_mov_b64 s[36:37], s[38:39]
	s_cbranch_scc0 .LBB0_1951
	s_and_b64 vcc, exec, s[16:17]
	s_cbranch_vccz .LBB0_1954
	s_barrier
